# code placement: s_nop pads in the load segments so every K-loop MFMA block starts 8-byte aligned
# speedup vs baseline: 1.0048x; 1.0048x over previous
; #define PG8_STAGE(bufoff, gbase, voff) do { _Pragma("unroll") for (int _i = 0; _i < 2; ++_i) \
;         __builtin_amdgcn_global_load_lds((const unsigned*)((const char*)(gbase) + (voff)[_i]), (PG8_LAS unsigned*)(lds + (bufoff) + ldsw + _i * 8192), 16, 0, 0); } while (0)
; #define PG8_LDA(dst, b, h) do { _Pragma("unroll") for (int m = 0; m < 4; ++m) _Pragma("unroll") for (int k = 0; k < 2; ++k) dst[m][k] = *(const PG8_LAS bf16x8*)(lds + PG8_SA(b, h) + aoff + m * 2048 + k * 1024); } while (0)
; #define PG8_LDB(dst, b, h) do { _Pragma("unroll") for (int n = 0; n < 2; ++n) _Pragma("unroll") for (int k = 0; k < 2; ++k) dst[n][k] = *(const PG8_LAS bf16x8*)(lds + PG8_SB(b, h) + boff + n * 2048 + k * 1024); } while (0)
; #define PG8_MMA(ai, bj, At, Bt) do { __builtin_amdgcn_s_setprio(1); _Pragma("unroll") for (int m = 0; m < 4; ++m) _Pragma("unroll") for (int n = 0; n < 2; ++n) _Pragma("unroll") for (int k = 0; k < 2; ++k) \
;         acc[ai][bj][m][n] = __builtin_amdgcn_mfma_f32_16x16x32_bf16(Bt[n][k], At[m][k], acc[ai][bj][m][n], 0, 0, 0); __builtin_amdgcn_s_setprio(0); } while (0)
; #define PG8_WAIT_V(n) asm volatile("s_waitcnt vmcnt(" #n ")" ::: "memory")
; #define PG8_WAIT_L(n) asm volatile("s_waitcnt lgkmcnt(" #n ")" ::: "memory")
; #define PG8_BAR __builtin_amdgcn_s_barrier()
; #define PG8_SCHED __builtin_amdgcn_sched_barrier(0)
; template <class Epi, class Sched, bool ALIGN_EPI = false, bool SP2 = false>
; __device__ __forceinline__ void gemm_phase(PG8_LAS unsigned char* lds, const Gemm g, const Sched& S, const Epi& E) {
;     ...
;             PG8_LDB(B0, 0, 0); PG8_LDB(B1, 0, 1); PG8_SCHED; PG8_LDA(At, 0, 0); PG8_STAGE(PG8_SA(1, 1), a1 + hstep, voffA);
;             PG8_WAIT_V(8); PG8_WAIT_L(0); PG8_BAR; PG8_MMA(0, 0, At, B0); PG8_MMA(0, 1, At, B1); PG8_BAR; PG8_SCHED;
;             PG8_LDA(At, 0, 1); PG8_STAGE(PG8_SB(0, 0), b2, voffB); PG8_STAGE(PG8_SB(0, 1), b2 + hstep, voffB); PG8_STAGE(PG8_SA(0, 0), a2, voffA);
;             PG8_WAIT_V(8); PG8_WAIT_L(0); PG8_BAR; PG8_MMA(1, 0, At, B0); PG8_MMA(1, 1, At, B1); PG8_BAR; PG8_SCHED;
.LBB0_366:
	ds_read_b128 v[130:133], v228
	ds_read_b128 v[134:137], v228 offset:1024
	ds_read_b128 v[138:141], v228 offset:2048
	ds_read_b128 v[170:173], v228 offset:3072
	ds_read_b128 v[174:177], v229
	ds_read_b128 v[178:181], v229 offset:1024
	ds_read_b128 v[182:185], v229 offset:2048
	ds_read_b128 v[186:189], v229 offset:3072
	s_add_u32 s12, s10, 0xfff00080
	s_addc_u32 s13, s11, -1
	s_cmp_eq_u32 s80, 60
	s_cselect_b32 s15, s0, s13
	s_cselect_b32 s14, s1, s12
	s_cselect_b32 s13, s61, s77
	s_cselect_b32 s12, s69, s71
	s_add_i32 m0, s79, 0xc000
	ds_read_b128 v[190:193], v230
	ds_read_b128 v[194:197], v230 offset:1024
	ds_read_b128 v[198:201], v230 offset:2048
	ds_read_b128 v[202:205], v230 offset:3072
	ds_read_b128 v[206:209], v230 offset:4096
	ds_read_b128 v[210:213], v230 offset:5120
	ds_read_b128 v[214:217], v230 offset:6144
	ds_read_b128 v[218:221], v230 offset:7168
	global_load_lds_dwordx4 v164, s[10:11]
	s_add_i32 m0, s79, 0xe000
	s_nop 0
	global_load_lds_dwordx4 v166, s[10:11]
	s_nop 0
	s_waitcnt vmcnt(8)
	s_waitcnt lgkmcnt(0)
	s_barrier
	s_waitcnt lgkmcnt(0)
	v_mfma_f32_16x16x32_bf16 v[126:129], v[130:133], v[190:193], v[126:129]
	v_mfma_f32_16x16x32_bf16 v[126:129], v[134:137], v[194:197], v[126:129]
	v_mfma_f32_16x16x32_bf16 v[122:125], v[138:141], v[190:193], v[122:125]
	v_mfma_f32_16x16x32_bf16 v[122:125], v[170:173], v[194:197], v[122:125]
	v_mfma_f32_16x16x32_bf16 v[110:113], v[130:133], v[198:201], v[110:113]
	v_mfma_f32_16x16x32_bf16 v[110:113], v[134:137], v[202:205], v[110:113]
	v_mfma_f32_16x16x32_bf16 v[106:109], v[138:141], v[198:201], v[106:109]
	v_mfma_f32_16x16x32_bf16 v[106:109], v[170:173], v[202:205], v[106:109]
	v_mfma_f32_16x16x32_bf16 v[94:97], v[130:133], v[206:209], v[94:97]
	v_mfma_f32_16x16x32_bf16 v[94:97], v[134:137], v[210:213], v[94:97]
	v_mfma_f32_16x16x32_bf16 v[90:93], v[138:141], v[206:209], v[90:93]
	v_mfma_f32_16x16x32_bf16 v[90:93], v[170:173], v[210:213], v[90:93]
	v_mfma_f32_16x16x32_bf16 v[78:81], v[130:133], v[214:217], v[78:81]
	v_mfma_f32_16x16x32_bf16 v[78:81], v[134:137], v[218:221], v[78:81]
	v_mfma_f32_16x16x32_bf16 v[74:77], v[138:141], v[214:217], v[74:77]
	v_mfma_f32_16x16x32_bf16 v[74:77], v[170:173], v[218:221], v[74:77]
	v_mfma_f32_16x16x32_bf16 v[118:121], v[174:177], v[190:193], v[118:121]
	v_mfma_f32_16x16x32_bf16 v[118:121], v[178:181], v[194:197], v[118:121]
	v_mfma_f32_16x16x32_bf16 v[114:117], v[182:185], v[190:193], v[114:117]
	v_mfma_f32_16x16x32_bf16 v[114:117], v[186:189], v[194:197], v[114:117]
	v_mfma_f32_16x16x32_bf16 v[102:105], v[174:177], v[198:201], v[102:105]
	v_mfma_f32_16x16x32_bf16 v[102:105], v[178:181], v[202:205], v[102:105]
	v_mfma_f32_16x16x32_bf16 v[98:101], v[182:185], v[198:201], v[98:101]
	v_mfma_f32_16x16x32_bf16 v[98:101], v[186:189], v[202:205], v[98:101]
	v_mfma_f32_16x16x32_bf16 v[86:89], v[174:177], v[206:209], v[86:89]
	v_mfma_f32_16x16x32_bf16 v[86:89], v[178:181], v[210:213], v[86:89]
	v_mfma_f32_16x16x32_bf16 v[82:85], v[182:185], v[206:209], v[82:85]
	v_mfma_f32_16x16x32_bf16 v[82:85], v[186:189], v[210:213], v[82:85]
	v_mfma_f32_16x16x32_bf16 v[70:73], v[174:177], v[214:217], v[70:73]
	v_mfma_f32_16x16x32_bf16 v[70:73], v[178:181], v[218:221], v[70:73]
	v_mfma_f32_16x16x32_bf16 v[66:69], v[182:185], v[214:217], v[66:69]
	v_mfma_f32_16x16x32_bf16 v[66:69], v[186:189], v[218:221], v[66:69]
	s_barrier
	s_add_i32 s81, s63, s67
	s_mov_b32 m0, s81
	ds_read_b128 v[190:193], v230 offset:16384
	ds_read_b128 v[194:197], v230 offset:17408
	ds_read_b128 v[198:201], v230 offset:18432
	ds_read_b128 v[202:205], v230 offset:19456
	ds_read_b128 v[206:209], v230 offset:20480
	ds_read_b128 v[210:213], v230 offset:21504
	ds_read_b128 v[214:217], v230 offset:22528
	ds_read_b128 v[218:221], v230 offset:23552
	global_load_lds_dwordx4 v144, s[12:13]
	s_add_i32 m0, s81, 0x2000
	s_add_u32 s82, s12, 0x100000
	s_addc_u32 s83, s13, 0
	s_add_i32 s81, s94, s67
	global_load_lds_dwordx4 v148, s[12:13]
	s_mov_b32 m0, s81
	s_nop 0
	global_load_lds_dwordx4 v144, s[82:83]
	s_add_i32 m0, s81, 0x2000
	s_nop 0
	global_load_lds_dwordx4 v148, s[82:83]
	s_mov_b32 m0, s79
	s_nop 0
	global_load_lds_dwordx4 v142, s[14:15]
	s_mov_b32 m0, s88
	s_nop 0
	global_load_lds_dwordx4 v146, s[14:15]
	s_waitcnt vmcnt(8)
	s_waitcnt lgkmcnt(0)
	s_barrier
	s_waitcnt lgkmcnt(0)
	v_mfma_f32_16x16x32_bf16 v[62:65], v[130:133], v[190:193], v[62:65]
	v_mfma_f32_16x16x32_bf16 v[62:65], v[134:137], v[194:197], v[62:65]
	v_mfma_f32_16x16x32_bf16 v[58:61], v[138:141], v[190:193], v[58:61]
	v_mfma_f32_16x16x32_bf16 v[58:61], v[170:173], v[194:197], v[58:61]
	v_mfma_f32_16x16x32_bf16 v[46:49], v[130:133], v[198:201], v[46:49]
	v_mfma_f32_16x16x32_bf16 v[46:49], v[134:137], v[202:205], v[46:49]
	v_mfma_f32_16x16x32_bf16 v[42:45], v[138:141], v[198:201], v[42:45]
	v_mfma_f32_16x16x32_bf16 v[42:45], v[170:173], v[202:205], v[42:45]
	v_mfma_f32_16x16x32_bf16 v[30:33], v[130:133], v[206:209], v[30:33]
	v_mfma_f32_16x16x32_bf16 v[30:33], v[134:137], v[210:213], v[30:33]
	v_mfma_f32_16x16x32_bf16 v[26:29], v[138:141], v[206:209], v[26:29]
	v_mfma_f32_16x16x32_bf16 v[26:29], v[170:173], v[210:213], v[26:29]
	v_mfma_f32_16x16x32_bf16 v[14:17], v[130:133], v[214:217], v[14:17]
	v_mfma_f32_16x16x32_bf16 v[14:17], v[134:137], v[218:221], v[14:17]
	v_mfma_f32_16x16x32_bf16 v[10:13], v[138:141], v[214:217], v[10:13]
	v_mfma_f32_16x16x32_bf16 v[10:13], v[170:173], v[218:221], v[10:13]
	v_mfma_f32_16x16x32_bf16 v[54:57], v[174:177], v[190:193], v[54:57]
	v_mfma_f32_16x16x32_bf16 v[54:57], v[178:181], v[194:197], v[54:57]
	v_mfma_f32_16x16x32_bf16 v[50:53], v[182:185], v[190:193], v[50:53]
	v_mfma_f32_16x16x32_bf16 v[50:53], v[186:189], v[194:197], v[50:53]
	v_mfma_f32_16x16x32_bf16 v[38:41], v[174:177], v[198:201], v[38:41]
	v_mfma_f32_16x16x32_bf16 v[38:41], v[178:181], v[202:205], v[38:41]
	v_mfma_f32_16x16x32_bf16 v[34:37], v[182:185], v[198:201], v[34:37]
	v_mfma_f32_16x16x32_bf16 v[34:37], v[186:189], v[202:205], v[34:37]
	v_mfma_f32_16x16x32_bf16 v[22:25], v[174:177], v[206:209], v[22:25]
	v_mfma_f32_16x16x32_bf16 v[22:25], v[178:181], v[210:213], v[22:25]
	v_mfma_f32_16x16x32_bf16 v[18:21], v[182:185], v[206:209], v[18:21]
	v_mfma_f32_16x16x32_bf16 v[18:21], v[186:189], v[210:213], v[18:21]
	v_mfma_f32_16x16x32_bf16 v[6:9], v[174:177], v[214:217], v[6:9]
	v_mfma_f32_16x16x32_bf16 v[6:9], v[178:181], v[218:221], v[6:9]
	v_mfma_f32_16x16x32_bf16 v[2:5], v[182:185], v[214:217], v[2:5]
	v_mfma_f32_16x16x32_bf16 v[2:5], v[186:189], v[218:221], v[2:5]
	s_barrier
; #define PG8_STAGE(bufoff, gbase, voff) do { _Pragma("unroll") for (int _i = 0; _i < 2; ++_i) \
;         __builtin_amdgcn_global_load_lds((const unsigned*)((const char*)(gbase) + (voff)[_i]), (PG8_LAS unsigned*)(lds + (bufoff) + ldsw + _i * 8192), 16, 0, 0); } while (0)
; #define PG8_LDA(dst, b, h) do { _Pragma("unroll") for (int m = 0; m < 4; ++m) _Pragma("unroll") for (int k = 0; k < 2; ++k) dst[m][k] = *(const PG8_LAS bf16x8*)(lds + PG8_SA(b, h) + aoff + m * 2048 + k * 1024); } while (0)
; #define PG8_LDB(dst, b, h) do { _Pragma("unroll") for (int n = 0; n < 2; ++n) _Pragma("unroll") for (int k = 0; k < 2; ++k) dst[n][k] = *(const PG8_LAS bf16x8*)(lds + PG8_SB(b, h) + boff + n * 2048 + k * 1024); } while (0)
; #define PG8_MMA(ai, bj, At, Bt) do { __builtin_amdgcn_s_setprio(1); _Pragma("unroll") for (int m = 0; m < 4; ++m) _Pragma("unroll") for (int n = 0; n < 2; ++n) _Pragma("unroll") for (int k = 0; k < 2; ++k) \
;         acc[ai][bj][m][n] = __builtin_amdgcn_mfma_f32_16x16x32_bf16(Bt[n][k], At[m][k], acc[ai][bj][m][n], 0, 0, 0); __builtin_amdgcn_s_setprio(0); } while (0)
; #define PG8_WAIT_V(n) asm volatile("s_waitcnt vmcnt(" #n ")" ::: "memory")
; #define PG8_WAIT_L(n) asm volatile("s_waitcnt lgkmcnt(" #n ")" ::: "memory")
; #define PG8_BAR __builtin_amdgcn_s_barrier()
; #define PG8_SCHED __builtin_amdgcn_sched_barrier(0)
; template <class Epi, class Sched, bool ALIGN_EPI = false, bool SP2 = false>
; __device__ __forceinline__ void gemm_phase(PG8_LAS unsigned char* lds, const Gemm g, const Sched& S, const Epi& E) {
;     ...
;         for (int t = 0; t < ntc; t += 2) {
;             if constexpr (Epi::MID) { if (ntc == nt && t == (nt >> 1)) E.mid(acc, cur, wr, wc, fr, fq); }
;             const bool last = (t == ntc - 2);
;     ...
;             PG8_LDB(B0, 1, 0); PG8_LDB(B1, 1, 1); PG8_SCHED; PG8_LDA(At, 1, 0); PG8_STAGE(PG8_SA(0, 1), a2 + hstep, voffA);
;             PG8_WAIT_V(8); PG8_WAIT_L(0); PG8_BAR; PG8_MMA(0, 0, At, B0); PG8_MMA(0, 1, At, B1); PG8_BAR; PG8_SCHED;
;             PG8_LDA(At, 1, 1); PG8_STAGE(PG8_SB(1, 0), b3, voffB); PG8_STAGE(PG8_SB(1, 1), b3 + hstep, voffB); PG8_STAGE(PG8_SA(1, 0), a3, voffA);
;             PG8_WAIT_V(8); PG8_WAIT_L(0); PG8_BAR; PG8_MMA(1, 0, At, B0); PG8_MMA(1, 1, At, B1); PG8_BAR; PG8_SCHED;
	s_add_i32 s81, 0, 0x18000
	v_add_u32_e32 v150, s81, v153
	s_add_i32 s82, 0, 0x1c000
	ds_read_b128 v[130:133], v150
	ds_read_b128 v[134:137], v150 offset:1024
	ds_read_b128 v[138:141], v150 offset:2048
	ds_read_b128 v[170:173], v150 offset:3072
	v_add_u32_e32 v150, s82, v153
	ds_read_b128 v[174:177], v150
	ds_read_b128 v[178:181], v150 offset:1024
	ds_read_b128 v[182:185], v150 offset:2048
	ds_read_b128 v[186:189], v150 offset:3072
	s_add_u32 s14, s14, 0x100000
	s_addc_u32 s15, s15, 0
	s_mov_b32 m0, s89
	ds_read_b128 v[190:193], v230 offset:32768
	ds_read_b128 v[194:197], v230 offset:33792
	ds_read_b128 v[198:201], v230 offset:34816
	ds_read_b128 v[202:205], v230 offset:35840
	ds_read_b128 v[206:209], v230 offset:36864
	ds_read_b128 v[210:213], v230 offset:37888
	ds_read_b128 v[214:217], v230 offset:38912
	ds_read_b128 v[218:221], v230 offset:39936
	global_load_lds_dwordx4 v142, s[14:15]
	s_mov_b32 m0, s90
	s_nop 0
	global_load_lds_dwordx4 v146, s[14:15]
	s_nop 0
	s_waitcnt vmcnt(8)
	s_waitcnt lgkmcnt(0)
	s_barrier
	s_waitcnt lgkmcnt(0)
	v_mfma_f32_16x16x32_bf16 v[126:129], v[130:133], v[190:193], v[126:129]
	v_mfma_f32_16x16x32_bf16 v[126:129], v[134:137], v[194:197], v[126:129]
	v_mfma_f32_16x16x32_bf16 v[122:125], v[138:141], v[190:193], v[122:125]
	v_mfma_f32_16x16x32_bf16 v[122:125], v[170:173], v[194:197], v[122:125]
	v_mfma_f32_16x16x32_bf16 v[110:113], v[130:133], v[198:201], v[110:113]
	v_mfma_f32_16x16x32_bf16 v[110:113], v[134:137], v[202:205], v[110:113]
	v_mfma_f32_16x16x32_bf16 v[106:109], v[138:141], v[198:201], v[106:109]
	v_mfma_f32_16x16x32_bf16 v[106:109], v[170:173], v[202:205], v[106:109]
	v_mfma_f32_16x16x32_bf16 v[94:97], v[130:133], v[206:209], v[94:97]
	v_mfma_f32_16x16x32_bf16 v[94:97], v[134:137], v[210:213], v[94:97]
	v_mfma_f32_16x16x32_bf16 v[90:93], v[138:141], v[206:209], v[90:93]
	v_mfma_f32_16x16x32_bf16 v[90:93], v[170:173], v[210:213], v[90:93]
	v_mfma_f32_16x16x32_bf16 v[78:81], v[130:133], v[214:217], v[78:81]
	v_mfma_f32_16x16x32_bf16 v[78:81], v[134:137], v[218:221], v[78:81]
	v_mfma_f32_16x16x32_bf16 v[74:77], v[138:141], v[214:217], v[74:77]
	v_mfma_f32_16x16x32_bf16 v[74:77], v[170:173], v[218:221], v[74:77]
	v_mfma_f32_16x16x32_bf16 v[118:121], v[174:177], v[190:193], v[118:121]
	v_mfma_f32_16x16x32_bf16 v[118:121], v[178:181], v[194:197], v[118:121]
	v_mfma_f32_16x16x32_bf16 v[114:117], v[182:185], v[190:193], v[114:117]
	v_mfma_f32_16x16x32_bf16 v[114:117], v[186:189], v[194:197], v[114:117]
	v_mfma_f32_16x16x32_bf16 v[102:105], v[174:177], v[198:201], v[102:105]
	v_mfma_f32_16x16x32_bf16 v[102:105], v[178:181], v[202:205], v[102:105]
	v_mfma_f32_16x16x32_bf16 v[98:101], v[182:185], v[198:201], v[98:101]
	v_mfma_f32_16x16x32_bf16 v[98:101], v[186:189], v[202:205], v[98:101]
	v_mfma_f32_16x16x32_bf16 v[86:89], v[174:177], v[206:209], v[86:89]
	v_mfma_f32_16x16x32_bf16 v[86:89], v[178:181], v[210:213], v[86:89]
	v_mfma_f32_16x16x32_bf16 v[82:85], v[182:185], v[206:209], v[82:85]
	v_mfma_f32_16x16x32_bf16 v[82:85], v[186:189], v[210:213], v[82:85]
	v_mfma_f32_16x16x32_bf16 v[70:73], v[174:177], v[214:217], v[70:73]
	v_mfma_f32_16x16x32_bf16 v[70:73], v[178:181], v[218:221], v[70:73]
	v_mfma_f32_16x16x32_bf16 v[66:69], v[182:185], v[214:217], v[66:69]
	v_mfma_f32_16x16x32_bf16 v[66:69], v[186:189], v[218:221], v[66:69]
	s_barrier
	s_add_u32 s100, s14, 0xfff00080
	s_addc_u32 s101, s15, -1
	s_add_u32 s98, s12, 0x80
	s_addc_u32 s99, s13, 0
	s_add_i32 s14, s81, s67
	s_mov_b32 m0, s14
	ds_read_b128 v[190:193], v230 offset:49152
	ds_read_b128 v[194:197], v230 offset:50176
	ds_read_b128 v[198:201], v230 offset:51200
	ds_read_b128 v[202:205], v230 offset:52224
	ds_read_b128 v[206:209], v230 offset:53248
	ds_read_b128 v[210:213], v230 offset:54272
	ds_read_b128 v[214:217], v230 offset:55296
	ds_read_b128 v[218:221], v230 offset:56320
	global_load_lds_dwordx4 v144, s[98:99]
	s_add_i32 m0, s14, 0x2000
	s_add_u32 s12, s12, 0x100080
	s_addc_u32 s13, s13, 0
	s_add_i32 s14, s82, s67
	global_load_lds_dwordx4 v148, s[98:99]
	s_mov_b32 m0, s14
	s_nop 0
	global_load_lds_dwordx4 v144, s[12:13]
	s_add_i32 m0, s14, 0x2000
	s_nop 0
	global_load_lds_dwordx4 v148, s[12:13]
	s_mov_b32 m0, s93
	s_nop 0
	global_load_lds_dwordx4 v142, s[100:101]
	s_mov_b32 m0, s62
	s_nop 0
	global_load_lds_dwordx4 v146, s[100:101]
	s_waitcnt vmcnt(8)
	s_waitcnt lgkmcnt(0)
	s_barrier
	s_waitcnt lgkmcnt(0)
	v_mfma_f32_16x16x32_bf16 v[62:65], v[130:133], v[190:193], v[62:65]
	v_mfma_f32_16x16x32_bf16 v[62:65], v[134:137], v[194:197], v[62:65]
	v_mfma_f32_16x16x32_bf16 v[58:61], v[138:141], v[190:193], v[58:61]
	v_mfma_f32_16x16x32_bf16 v[58:61], v[170:173], v[194:197], v[58:61]
	v_mfma_f32_16x16x32_bf16 v[46:49], v[130:133], v[198:201], v[46:49]
	v_mfma_f32_16x16x32_bf16 v[46:49], v[134:137], v[202:205], v[46:49]
	v_mfma_f32_16x16x32_bf16 v[42:45], v[138:141], v[198:201], v[42:45]
	v_mfma_f32_16x16x32_bf16 v[42:45], v[170:173], v[202:205], v[42:45]
	v_mfma_f32_16x16x32_bf16 v[30:33], v[130:133], v[206:209], v[30:33]
	v_mfma_f32_16x16x32_bf16 v[30:33], v[134:137], v[210:213], v[30:33]
	v_mfma_f32_16x16x32_bf16 v[26:29], v[138:141], v[206:209], v[26:29]
	v_mfma_f32_16x16x32_bf16 v[26:29], v[170:173], v[210:213], v[26:29]
	v_mfma_f32_16x16x32_bf16 v[14:17], v[130:133], v[214:217], v[14:17]
	v_mfma_f32_16x16x32_bf16 v[14:17], v[134:137], v[218:221], v[14:17]
	v_mfma_f32_16x16x32_bf16 v[10:13], v[138:141], v[214:217], v[10:13]
	v_mfma_f32_16x16x32_bf16 v[10:13], v[170:173], v[218:221], v[10:13]
	v_mfma_f32_16x16x32_bf16 v[54:57], v[174:177], v[190:193], v[54:57]
	v_mfma_f32_16x16x32_bf16 v[54:57], v[178:181], v[194:197], v[54:57]
	v_mfma_f32_16x16x32_bf16 v[50:53], v[182:185], v[190:193], v[50:53]
	v_mfma_f32_16x16x32_bf16 v[50:53], v[186:189], v[194:197], v[50:53]
	v_mfma_f32_16x16x32_bf16 v[38:41], v[174:177], v[198:201], v[38:41]
	v_mfma_f32_16x16x32_bf16 v[38:41], v[178:181], v[202:205], v[38:41]
	v_mfma_f32_16x16x32_bf16 v[34:37], v[182:185], v[198:201], v[34:37]
	v_mfma_f32_16x16x32_bf16 v[34:37], v[186:189], v[202:205], v[34:37]
	v_mfma_f32_16x16x32_bf16 v[22:25], v[174:177], v[206:209], v[22:25]
	v_mfma_f32_16x16x32_bf16 v[22:25], v[178:181], v[210:213], v[22:25]
	v_mfma_f32_16x16x32_bf16 v[18:21], v[182:185], v[206:209], v[18:21]
	v_mfma_f32_16x16x32_bf16 v[18:21], v[186:189], v[210:213], v[18:21]
	v_mfma_f32_16x16x32_bf16 v[6:9], v[174:177], v[214:217], v[6:9]
	v_mfma_f32_16x16x32_bf16 v[6:9], v[178:181], v[218:221], v[6:9]
	v_mfma_f32_16x16x32_bf16 v[2:5], v[182:185], v[214:217], v[2:5]
	v_mfma_f32_16x16x32_bf16 v[2:5], v[186:189], v[218:221], v[2:5]
	s_barrier
	s_add_i32 s80, s80, 2
	s_add_u32 s10, s10, 0x100
	s_addc_u32 s11, s11, 0
	s_add_u32 s71, s71, 0x100
	s_addc_u32 s77, s77, 0
	s_cmp_gt_u32 s80, 61
	s_cbranch_scc0 .LBB0_366
	s_and_b64 vcc, exec, s[28:29]
	s_cbranch_vccz .LBB0_369
	s_barrier

; #define PG8_STAGE(bufoff, gbase, voff) do { _Pragma("unroll") for (int _i = 0; _i < 2; ++_i) \
;         __builtin_amdgcn_global_load_lds((const unsigned*)((const char*)(gbase) + (voff)[_i]), (PG8_LAS unsigned*)(lds + (bufoff) + ldsw + _i * 8192), 16, 0, 0); } while (0)
; #define PG8_LDA(dst, b, h) do { _Pragma("unroll") for (int m = 0; m < 4; ++m) _Pragma("unroll") for (int k = 0; k < 2; ++k) dst[m][k] = *(const PG8_LAS bf16x8*)(lds + PG8_SA(b, h) + aoff + m * 2048 + k * 1024); } while (0)
; #define PG8_LDB(dst, b, h) do { _Pragma("unroll") for (int n = 0; n < 2; ++n) _Pragma("unroll") for (int k = 0; k < 2; ++k) dst[n][k] = *(const PG8_LAS bf16x8*)(lds + PG8_SB(b, h) + boff + n * 2048 + k * 1024); } while (0)
; #define PG8_WAIT_V(n) asm volatile("s_waitcnt vmcnt(" #n ")" ::: "memory")
; #define PG8_WAIT_L(n) asm volatile("s_waitcnt lgkmcnt(" #n ")" ::: "memory")
; template <class Epi, class Sched, bool ALIGN_EPI = false, bool SP2 = false>
; __device__ __forceinline__ void gemm_phase(PG8_LAS unsigned char* lds, const Gemm g, const Sched& S, const Epi& E) {
;     ...
;         const char* nA = has_next ? (const char*)g.A + (size_t)nxt.pm * tstep + (size_t)nxt.kt0 * kstep : cA; const char* nB = has_next ? (const char*)g.Bt + (size_t)nxt.pn * tstep + (size_t)nxt.kt0 * kstep : cB;
;         const int ntc = cur.ntu;
;         for (int t = 0; t < ntc; t += 2) {
;             if constexpr (Epi::MID) { if (ntc == nt && t == (nt >> 1)) E.mid(acc, cur, wr, wc, fr, fq); }
;             const bool last = (t == ntc - 2);
;             const char* a1 = cA + (size_t)(t + 1) * kstep;
;             const char* a2 = last ? nA : cA + (size_t)(t + 2) * kstep; const char* b2 = last ? nB : cB + (size_t)(t + 2) * kstep;
;             const char* a3 = a2 + kstep; const char* b3 = b2 + kstep;
;             if (last && has_next) S.a_ready(nxt);
;             if constexpr (SP2) {
;             PG8_LDB(B0, 0, 0); PG8_LDB(B1, 0, 1); PG8_SCHED; PG8_LDA(At, 0, 0); PG8_STAGE(PG8_SA(1, 1), a1 + hstep, voffA);
;             PG8_WAIT_V(8); PG8_WAIT_L(0); PG8_BAR; PG8_MMA(0, 0, At, B0); PG8_MMA(0, 1, At, B1); PG8_BAR; PG8_SCHED;
;             PG8_LDA(At, 0, 1); PG8_STAGE(PG8_SB(0, 0), b2, voffB); PG8_STAGE(PG8_SB(0, 1), b2 + hstep, voffB); PG8_STAGE(PG8_SA(0, 0), a2, voffA);
;             PG8_WAIT_V(8); PG8_WAIT_L(0); PG8_BAR; PG8_MMA(1, 0, At, B0); PG8_MMA(1, 1, At, B1); PG8_BAR; PG8_SCHED;
.LBB0_2487:
	v_add_u32_e32 v3, s67, v183
	s_add_i32 s81, s50, 2
	ds_read_b128 v[154:157], v3
	ds_read_b128 v[158:161], v3 offset:1024
	ds_read_b128 v[162:165], v3 offset:2048
	ds_read_b128 v[166:169], v3 offset:3072
	v_add_u32_e32 v3, s68, v183
	s_add_u32 s51, s42, s46
	ds_read_b128 v[170:173], v3
	ds_read_b128 v[174:177], v3 offset:1024
	ds_read_b128 v[178:181], v3 offset:2048
	ds_read_b128 v[184:187], v3 offset:3072
	s_addc_u32 s52, s43, s47
	s_add_u32 s51, s51, 0x100
	s_addc_u32 s52, s52, 0
	s_add_u32 s82, s79, s46
	s_addc_u32 s83, s80, s47
	s_cmp_eq_u32 s9, s50
	s_cselect_b32 s53, s27, s52
	s_cselect_b32 s52, s35, s51
	s_cselect_b32 s51, s31, s83
	s_cselect_b32 s50, s78, s82
	v_lshl_add_u64 v[4:5], v[150:151], 0, s[46:47]
	s_add_i32 m0, s11, 0xc000
	ds_read_b128 v[188:191], v211
	ds_read_b128 v[192:195], v211 offset:1024
	ds_read_b128 v[196:199], v211 offset:2048
	ds_read_b128 v[200:203], v211 offset:3072
	ds_read_b128 v[204:207], v211 offset:4096
	ds_read_b128 v[212:215], v211 offset:5120
	ds_read_b128 v[216:219], v211 offset:6144
	ds_read_b128 v[220:223], v211 offset:7168
	global_load_lds_dwordx4 v[4:5], off
	v_lshl_add_u64 v[4:5], v[152:153], 0, s[46:47]
	s_add_i32 m0, s11, 0xe000
	s_nop 0
	global_load_lds_dwordx4 v[4:5], off
	s_waitcnt vmcnt(8)
	s_waitcnt lgkmcnt(0)
	s_barrier
	s_waitcnt lgkmcnt(0)
	v_mfma_f32_16x16x32_bf16 v[130:133], v[154:157], v[188:191], v[130:133]
	v_mfma_f32_16x16x32_bf16 v[130:133], v[158:161], v[192:195], v[130:133]
	v_mfma_f32_16x16x32_bf16 v[126:129], v[162:165], v[188:191], v[126:129]
	v_mfma_f32_16x16x32_bf16 v[126:129], v[166:169], v[192:195], v[126:129]
	v_mfma_f32_16x16x32_bf16 v[114:117], v[154:157], v[196:199], v[114:117]
	v_mfma_f32_16x16x32_bf16 v[114:117], v[158:161], v[200:203], v[114:117]
	v_mfma_f32_16x16x32_bf16 v[110:113], v[162:165], v[196:199], v[110:113]
	v_mfma_f32_16x16x32_bf16 v[110:113], v[166:169], v[200:203], v[110:113]
	v_mfma_f32_16x16x32_bf16 v[98:101], v[154:157], v[204:207], v[98:101]
	v_mfma_f32_16x16x32_bf16 v[98:101], v[158:161], v[212:215], v[98:101]
	v_mfma_f32_16x16x32_bf16 v[94:97], v[162:165], v[204:207], v[94:97]
	v_mfma_f32_16x16x32_bf16 v[94:97], v[166:169], v[212:215], v[94:97]
	v_mfma_f32_16x16x32_bf16 v[82:85], v[154:157], v[216:219], v[82:85]
	v_mfma_f32_16x16x32_bf16 v[82:85], v[158:161], v[220:223], v[82:85]
	v_mfma_f32_16x16x32_bf16 v[78:81], v[162:165], v[216:219], v[78:81]
	v_mfma_f32_16x16x32_bf16 v[78:81], v[166:169], v[220:223], v[78:81]
	v_mfma_f32_16x16x32_bf16 v[122:125], v[170:173], v[188:191], v[122:125]
	v_mfma_f32_16x16x32_bf16 v[122:125], v[174:177], v[192:195], v[122:125]
	v_mfma_f32_16x16x32_bf16 v[118:121], v[178:181], v[188:191], v[118:121]
	v_mfma_f32_16x16x32_bf16 v[118:121], v[184:187], v[192:195], v[118:121]
	v_mfma_f32_16x16x32_bf16 v[106:109], v[170:173], v[196:199], v[106:109]
	v_mfma_f32_16x16x32_bf16 v[106:109], v[174:177], v[200:203], v[106:109]
	v_mfma_f32_16x16x32_bf16 v[102:105], v[178:181], v[196:199], v[102:105]
	v_mfma_f32_16x16x32_bf16 v[102:105], v[184:187], v[200:203], v[102:105]
	v_mfma_f32_16x16x32_bf16 v[90:93], v[170:173], v[204:207], v[90:93]
	v_mfma_f32_16x16x32_bf16 v[90:93], v[174:177], v[212:215], v[90:93]
	v_mfma_f32_16x16x32_bf16 v[86:89], v[178:181], v[204:207], v[86:89]
	v_mfma_f32_16x16x32_bf16 v[86:89], v[184:187], v[212:215], v[86:89]
	v_mfma_f32_16x16x32_bf16 v[74:77], v[170:173], v[216:219], v[74:77]
	v_mfma_f32_16x16x32_bf16 v[74:77], v[174:177], v[220:223], v[74:77]
	v_mfma_f32_16x16x32_bf16 v[70:73], v[178:181], v[216:219], v[70:73]
	v_mfma_f32_16x16x32_bf16 v[70:73], v[184:187], v[220:223], v[70:73]
	s_barrier
	s_add_i32 s82, s67, s55
	s_mov_b32 m0, s82
	ds_read_b128 v[188:191], v211 offset:16384
	ds_read_b128 v[192:195], v211 offset:17408
	ds_read_b128 v[196:199], v211 offset:18432
	ds_read_b128 v[200:203], v211 offset:19456
	ds_read_b128 v[204:207], v211 offset:20480
	ds_read_b128 v[212:215], v211 offset:21504
	ds_read_b128 v[216:219], v211 offset:22528
	ds_read_b128 v[220:223], v211 offset:23552
	global_load_lds_dwordx4 v134, s[50:51]
	s_add_i32 m0, s82, 0x2000
	s_add_u32 s82, s50, 0x100000
	s_addc_u32 s83, s51, 0
	s_add_i32 s84, s68, s55
	global_load_lds_dwordx4 v136, s[50:51]
	s_mov_b32 m0, s84
	s_nop 0
	global_load_lds_dwordx4 v134, s[82:83]
	s_add_i32 m0, s84, 0x2000
	s_nop 0
	global_load_lds_dwordx4 v136, s[82:83]
	s_mov_b32 m0, s11
	s_nop 0
	global_load_lds_dwordx4 v134, s[52:53]
	s_mov_b32 m0, s57
	s_nop 0
	global_load_lds_dwordx4 v136, s[52:53]
	s_waitcnt vmcnt(8)
	s_waitcnt lgkmcnt(0)
	s_barrier
; #define PG8_STAGE(bufoff, gbase, voff) do { _Pragma("unroll") for (int _i = 0; _i < 2; ++_i) \
;         __builtin_amdgcn_global_load_lds((const unsigned*)((const char*)(gbase) + (voff)[_i]), (PG8_LAS unsigned*)(lds + (bufoff) + ldsw + _i * 8192), 16, 0, 0); } while (0)
; #define PG8_LDA(dst, b, h) do { _Pragma("unroll") for (int m = 0; m < 4; ++m) _Pragma("unroll") for (int k = 0; k < 2; ++k) dst[m][k] = *(const PG8_LAS bf16x8*)(lds + PG8_SA(b, h) + aoff + m * 2048 + k * 1024); } while (0)
; #define PG8_LDB(dst, b, h) do { _Pragma("unroll") for (int n = 0; n < 2; ++n) _Pragma("unroll") for (int k = 0; k < 2; ++k) dst[n][k] = *(const PG8_LAS bf16x8*)(lds + PG8_SB(b, h) + boff + n * 2048 + k * 1024); } while (0)
; #define PG8_MMA(ai, bj, At, Bt) do { __builtin_amdgcn_s_setprio(1); _Pragma("unroll") for (int m = 0; m < 4; ++m) _Pragma("unroll") for (int n = 0; n < 2; ++n) _Pragma("unroll") for (int k = 0; k < 2; ++k) \
;         acc[ai][bj][m][n] = __builtin_amdgcn_mfma_f32_16x16x32_bf16(Bt[n][k], At[m][k], acc[ai][bj][m][n], 0, 0, 0); __builtin_amdgcn_s_setprio(0); } while (0)
; #define PG8_WAIT_V(n) asm volatile("s_waitcnt vmcnt(" #n ")" ::: "memory")
; #define PG8_WAIT_L(n) asm volatile("s_waitcnt lgkmcnt(" #n ")" ::: "memory")
; #define PG8_BAR __builtin_amdgcn_s_barrier()
; #define PG8_SCHED __builtin_amdgcn_sched_barrier(0)
; template <class Epi, class Sched, bool ALIGN_EPI = false, bool SP2 = false>
; __device__ __forceinline__ void gemm_phase(PG8_LAS unsigned char* lds, const Gemm g, const Sched& S, const Epi& E) {
;     ...
;             PG8_WAIT_V(8); PG8_WAIT_L(0); PG8_BAR; PG8_MMA(1, 0, At, B0); PG8_MMA(1, 1, At, B1); PG8_BAR; PG8_SCHED;
;             PG8_LDB(B0, 1, 0); PG8_LDB(B1, 1, 1); PG8_SCHED; PG8_LDA(At, 1, 0); PG8_STAGE(PG8_SA(0, 1), a2 + hstep, voffA);
;             PG8_WAIT_V(8); PG8_WAIT_L(0); PG8_BAR; PG8_MMA(0, 0, At, B0); PG8_MMA(0, 1, At, B1); PG8_BAR; PG8_SCHED;
	s_waitcnt lgkmcnt(0)
	v_mfma_f32_16x16x32_bf16 v[66:69], v[154:157], v[188:191], v[66:69]
	v_mfma_f32_16x16x32_bf16 v[66:69], v[158:161], v[192:195], v[66:69]
	v_mfma_f32_16x16x32_bf16 v[62:65], v[162:165], v[188:191], v[62:65]
	v_mfma_f32_16x16x32_bf16 v[62:65], v[166:169], v[192:195], v[62:65]
	v_mfma_f32_16x16x32_bf16 v[50:53], v[154:157], v[196:199], v[50:53]
	v_mfma_f32_16x16x32_bf16 v[50:53], v[158:161], v[200:203], v[50:53]
	v_mfma_f32_16x16x32_bf16 v[46:49], v[162:165], v[196:199], v[46:49]
	v_mfma_f32_16x16x32_bf16 v[46:49], v[166:169], v[200:203], v[46:49]
	v_mfma_f32_16x16x32_bf16 v[34:37], v[154:157], v[204:207], v[34:37]
	v_mfma_f32_16x16x32_bf16 v[34:37], v[158:161], v[212:215], v[34:37]
	v_mfma_f32_16x16x32_bf16 v[30:33], v[162:165], v[204:207], v[30:33]
	v_mfma_f32_16x16x32_bf16 v[30:33], v[166:169], v[212:215], v[30:33]
	v_mfma_f32_16x16x32_bf16 v[18:21], v[154:157], v[216:219], v[18:21]
	v_mfma_f32_16x16x32_bf16 v[18:21], v[158:161], v[220:223], v[18:21]
	v_mfma_f32_16x16x32_bf16 v[14:17], v[162:165], v[216:219], v[14:17]
	v_mfma_f32_16x16x32_bf16 v[14:17], v[166:169], v[220:223], v[14:17]
	v_mfma_f32_16x16x32_bf16 v[58:61], v[170:173], v[188:191], v[58:61]
	v_mfma_f32_16x16x32_bf16 v[58:61], v[174:177], v[192:195], v[58:61]
	v_mfma_f32_16x16x32_bf16 v[54:57], v[178:181], v[188:191], v[54:57]
	v_mfma_f32_16x16x32_bf16 v[54:57], v[184:187], v[192:195], v[54:57]
	v_mfma_f32_16x16x32_bf16 v[42:45], v[170:173], v[196:199], v[42:45]
	v_mfma_f32_16x16x32_bf16 v[42:45], v[174:177], v[200:203], v[42:45]
	v_mfma_f32_16x16x32_bf16 v[38:41], v[178:181], v[196:199], v[38:41]
	v_mfma_f32_16x16x32_bf16 v[38:41], v[184:187], v[200:203], v[38:41]
	v_mfma_f32_16x16x32_bf16 v[26:29], v[170:173], v[204:207], v[26:29]
	v_mfma_f32_16x16x32_bf16 v[26:29], v[174:177], v[212:215], v[26:29]
	v_mfma_f32_16x16x32_bf16 v[22:25], v[178:181], v[204:207], v[22:25]
	v_mfma_f32_16x16x32_bf16 v[22:25], v[184:187], v[212:215], v[22:25]
	v_mfma_f32_16x16x32_bf16 v[10:13], v[170:173], v[216:219], v[10:13]
	v_mfma_f32_16x16x32_bf16 v[10:13], v[174:177], v[220:223], v[10:13]
	v_mfma_f32_16x16x32_bf16 v[4:7], v[178:181], v[216:219], v[6:9]
	v_mfma_f32_16x16x32_bf16 v[4:7], v[184:187], v[220:223], v[4:7]
	s_barrier
	s_add_i32 s82, 0, 0x18000
	v_add_u32_e32 v3, s82, v183
	s_add_i32 s83, 0, 0x1c000
	ds_read_b128 v[154:157], v3
	ds_read_b128 v[158:161], v3 offset:1024
	ds_read_b128 v[162:165], v3 offset:2048
	ds_read_b128 v[166:169], v3 offset:3072
	v_add_u32_e32 v3, s83, v183
	ds_read_b128 v[170:173], v3
	ds_read_b128 v[174:177], v3 offset:1024
	ds_read_b128 v[178:181], v3 offset:2048
	ds_read_b128 v[184:187], v3 offset:3072
	s_add_u32 s52, s52, 0x100000
	s_addc_u32 s53, s53, 0
	s_mov_b32 m0, s60
	ds_read_b128 v[188:191], v211 offset:32768
	ds_read_b128 v[192:195], v211 offset:33792
	ds_read_b128 v[196:199], v211 offset:34816
	ds_read_b128 v[200:203], v211 offset:35840
	ds_read_b128 v[204:207], v211 offset:36864
	ds_read_b128 v[212:215], v211 offset:37888
	ds_read_b128 v[216:219], v211 offset:38912
	ds_read_b128 v[220:223], v211 offset:39936
	global_load_lds_dwordx4 v134, s[52:53]
	s_mov_b32 m0, s61
	s_nop 0
	global_load_lds_dwordx4 v136, s[52:53]
	s_nop 0
	s_waitcnt vmcnt(8)
	s_waitcnt lgkmcnt(0)
	s_barrier
	s_waitcnt lgkmcnt(0)
	v_mfma_f32_16x16x32_bf16 v[130:133], v[154:157], v[188:191], v[130:133]
	v_mfma_f32_16x16x32_bf16 v[130:133], v[158:161], v[192:195], v[130:133]
	v_mfma_f32_16x16x32_bf16 v[126:129], v[162:165], v[188:191], v[126:129]
	v_mfma_f32_16x16x32_bf16 v[126:129], v[166:169], v[192:195], v[126:129]
	v_mfma_f32_16x16x32_bf16 v[114:117], v[154:157], v[196:199], v[114:117]
	v_mfma_f32_16x16x32_bf16 v[114:117], v[158:161], v[200:203], v[114:117]
	v_mfma_f32_16x16x32_bf16 v[110:113], v[162:165], v[196:199], v[110:113]
	v_mfma_f32_16x16x32_bf16 v[110:113], v[166:169], v[200:203], v[110:113]
	v_mfma_f32_16x16x32_bf16 v[98:101], v[154:157], v[204:207], v[98:101]
	v_mfma_f32_16x16x32_bf16 v[98:101], v[158:161], v[212:215], v[98:101]
	v_mfma_f32_16x16x32_bf16 v[94:97], v[162:165], v[204:207], v[94:97]
	v_mfma_f32_16x16x32_bf16 v[94:97], v[166:169], v[212:215], v[94:97]
	v_mfma_f32_16x16x32_bf16 v[82:85], v[154:157], v[216:219], v[82:85]
	v_mfma_f32_16x16x32_bf16 v[82:85], v[158:161], v[220:223], v[82:85]
	v_mfma_f32_16x16x32_bf16 v[78:81], v[162:165], v[216:219], v[78:81]
	v_mfma_f32_16x16x32_bf16 v[78:81], v[166:169], v[220:223], v[78:81]
	v_mfma_f32_16x16x32_bf16 v[122:125], v[170:173], v[188:191], v[122:125]
	v_mfma_f32_16x16x32_bf16 v[122:125], v[174:177], v[192:195], v[122:125]
	v_mfma_f32_16x16x32_bf16 v[118:121], v[178:181], v[188:191], v[118:121]
	v_mfma_f32_16x16x32_bf16 v[118:121], v[184:187], v[192:195], v[118:121]
	v_mfma_f32_16x16x32_bf16 v[106:109], v[170:173], v[196:199], v[106:109]
	v_mfma_f32_16x16x32_bf16 v[106:109], v[174:177], v[200:203], v[106:109]
	v_mfma_f32_16x16x32_bf16 v[102:105], v[178:181], v[196:199], v[102:105]
	v_mfma_f32_16x16x32_bf16 v[102:105], v[184:187], v[200:203], v[102:105]
	v_mfma_f32_16x16x32_bf16 v[90:93], v[170:173], v[204:207], v[90:93]
	v_mfma_f32_16x16x32_bf16 v[90:93], v[174:177], v[212:215], v[90:93]
	v_mfma_f32_16x16x32_bf16 v[86:89], v[178:181], v[204:207], v[86:89]
	v_mfma_f32_16x16x32_bf16 v[86:89], v[184:187], v[212:215], v[86:89]
	v_mfma_f32_16x16x32_bf16 v[74:77], v[170:173], v[216:219], v[74:77]
	v_mfma_f32_16x16x32_bf16 v[74:77], v[174:177], v[220:223], v[74:77]
	v_mfma_f32_16x16x32_bf16 v[70:73], v[178:181], v[216:219], v[70:73]
	v_mfma_f32_16x16x32_bf16 v[70:73], v[184:187], v[220:223], v[70:73]
	s_barrier
; #define PG8_STAGE(bufoff, gbase, voff) do { _Pragma("unroll") for (int _i = 0; _i < 2; ++_i) \
;         __builtin_amdgcn_global_load_lds((const unsigned*)((const char*)(gbase) + (voff)[_i]), (PG8_LAS unsigned*)(lds + (bufoff) + ldsw + _i * 8192), 16, 0, 0); } while (0)
; #define PG8_LDA(dst, b, h) do { _Pragma("unroll") for (int m = 0; m < 4; ++m) _Pragma("unroll") for (int k = 0; k < 2; ++k) dst[m][k] = *(const PG8_LAS bf16x8*)(lds + PG8_SA(b, h) + aoff + m * 2048 + k * 1024); } while (0)
; #define PG8_MMA(ai, bj, At, Bt) do { __builtin_amdgcn_s_setprio(1); _Pragma("unroll") for (int m = 0; m < 4; ++m) _Pragma("unroll") for (int n = 0; n < 2; ++n) _Pragma("unroll") for (int k = 0; k < 2; ++k) \
;         acc[ai][bj][m][n] = __builtin_amdgcn_mfma_f32_16x16x32_bf16(Bt[n][k], At[m][k], acc[ai][bj][m][n], 0, 0, 0); __builtin_amdgcn_s_setprio(0); } while (0)
; #define PG8_WAIT_V(n) asm volatile("s_waitcnt vmcnt(" #n ")" ::: "memory")
; #define PG8_WAIT_L(n) asm volatile("s_waitcnt lgkmcnt(" #n ")" ::: "memory")
; #define PG8_BAR __builtin_amdgcn_s_barrier()
; #define PG8_SCHED __builtin_amdgcn_sched_barrier(0)
; template <class Epi, class Sched, bool ALIGN_EPI = false, bool SP2 = false>
; __device__ __forceinline__ void gemm_phase(PG8_LAS unsigned char* lds, const Gemm g, const Sched& S, const Epi& E) {
;     ...
;         for (int t = 0; t < ntc; t += 2) {
;     ...
;             PG8_LDA(At, 1, 1); PG8_STAGE(PG8_SB(1, 0), b3, voffB); PG8_STAGE(PG8_SB(1, 1), b3 + hstep, voffB); PG8_STAGE(PG8_SA(1, 0), a3, voffA);
;             PG8_WAIT_V(8); PG8_WAIT_L(0); PG8_BAR; PG8_MMA(1, 0, At, B0); PG8_MMA(1, 1, At, B1); PG8_BAR; PG8_SCHED;
	s_add_u32 s100, s52, 0xfff00080
	s_addc_u32 s101, s53, -1
	s_add_u32 s98, s50, 0x80
	s_addc_u32 s99, s51, 0
	s_add_i32 s52, s82, s55
	s_mov_b32 m0, s52
	ds_read_b128 v[188:191], v211 offset:49152
	ds_read_b128 v[192:195], v211 offset:50176
	ds_read_b128 v[196:199], v211 offset:51200
	ds_read_b128 v[200:203], v211 offset:52224
	ds_read_b128 v[204:207], v211 offset:53248
	ds_read_b128 v[212:215], v211 offset:54272
	ds_read_b128 v[216:219], v211 offset:55296
	ds_read_b128 v[220:223], v211 offset:56320
	global_load_lds_dwordx4 v134, s[98:99]
	s_add_i32 m0, s52, 0x2000
	s_add_u32 s50, s50, 0x100080
	s_addc_u32 s51, s51, 0
	s_add_i32 s52, s83, s55
	global_load_lds_dwordx4 v136, s[98:99]
	s_mov_b32 m0, s52
	s_nop 0
	global_load_lds_dwordx4 v134, s[50:51]
	s_add_i32 m0, s52, 0x2000
	s_nop 0
	global_load_lds_dwordx4 v136, s[50:51]
	s_mov_b32 m0, s63
	s_nop 0
	global_load_lds_dwordx4 v134, s[100:101]
	s_mov_b32 m0, s64
	s_nop 0
	global_load_lds_dwordx4 v136, s[100:101]
	s_waitcnt vmcnt(8)
	s_waitcnt lgkmcnt(0)
	s_barrier
	s_waitcnt lgkmcnt(0)
	v_mfma_f32_16x16x32_bf16 v[66:69], v[154:157], v[188:191], v[66:69]
	v_mfma_f32_16x16x32_bf16 v[66:69], v[158:161], v[192:195], v[66:69]
	v_mfma_f32_16x16x32_bf16 v[62:65], v[162:165], v[188:191], v[62:65]
	v_mfma_f32_16x16x32_bf16 v[62:65], v[166:169], v[192:195], v[62:65]
	v_mfma_f32_16x16x32_bf16 v[50:53], v[154:157], v[196:199], v[50:53]
	v_mfma_f32_16x16x32_bf16 v[50:53], v[158:161], v[200:203], v[50:53]
	v_mfma_f32_16x16x32_bf16 v[46:49], v[162:165], v[196:199], v[46:49]
	v_mfma_f32_16x16x32_bf16 v[46:49], v[166:169], v[200:203], v[46:49]
	v_mfma_f32_16x16x32_bf16 v[34:37], v[154:157], v[204:207], v[34:37]
	v_mfma_f32_16x16x32_bf16 v[34:37], v[158:161], v[212:215], v[34:37]
	v_mfma_f32_16x16x32_bf16 v[30:33], v[162:165], v[204:207], v[30:33]
	v_mfma_f32_16x16x32_bf16 v[30:33], v[166:169], v[212:215], v[30:33]
	v_mfma_f32_16x16x32_bf16 v[18:21], v[154:157], v[216:219], v[18:21]
	v_mfma_f32_16x16x32_bf16 v[18:21], v[158:161], v[220:223], v[18:21]
	v_mfma_f32_16x16x32_bf16 v[14:17], v[162:165], v[216:219], v[14:17]
	v_mfma_f32_16x16x32_bf16 v[14:17], v[166:169], v[220:223], v[14:17]
	v_mfma_f32_16x16x32_bf16 v[58:61], v[170:173], v[188:191], v[58:61]
	v_mfma_f32_16x16x32_bf16 v[58:61], v[174:177], v[192:195], v[58:61]
	v_mfma_f32_16x16x32_bf16 v[54:57], v[178:181], v[188:191], v[54:57]
	v_mfma_f32_16x16x32_bf16 v[54:57], v[184:187], v[192:195], v[54:57]
	v_mfma_f32_16x16x32_bf16 v[42:45], v[170:173], v[196:199], v[42:45]
	v_mfma_f32_16x16x32_bf16 v[42:45], v[174:177], v[200:203], v[42:45]
	v_mfma_f32_16x16x32_bf16 v[38:41], v[178:181], v[196:199], v[38:41]
	v_mfma_f32_16x16x32_bf16 v[38:41], v[184:187], v[200:203], v[38:41]
	v_mfma_f32_16x16x32_bf16 v[26:29], v[170:173], v[204:207], v[26:29]
	v_mfma_f32_16x16x32_bf16 v[26:29], v[174:177], v[212:215], v[26:29]
	v_mfma_f32_16x16x32_bf16 v[22:25], v[178:181], v[204:207], v[22:25]
	v_mfma_f32_16x16x32_bf16 v[22:25], v[184:187], v[212:215], v[22:25]
	v_mfma_f32_16x16x32_bf16 v[8:11], v[170:173], v[216:219], v[10:13]
	v_mfma_f32_16x16x32_bf16 v[10:13], v[174:177], v[220:223], v[8:11]
	v_mfma_f32_16x16x32_bf16 v[4:7], v[178:181], v[216:219], v[4:7]
	v_mfma_f32_16x16x32_bf16 v[6:9], v[184:187], v[220:223], v[4:7]
	s_barrier
	s_add_u32 s46, s46, 0x100
	s_addc_u32 s47, s47, 0
	s_cmp_ge_i32 s81, s77
	s_cbranch_scc1 .LBB0_2489
	s_mov_b32 s50, s81
	s_branch .LBB0_2485

; #define PG8_STAGE(bufoff, gbase, voff) do { _Pragma("unroll") for (int _i = 0; _i < 2; ++_i) \
;         __builtin_amdgcn_global_load_lds((const unsigned*)((const char*)(gbase) + (voff)[_i]), (PG8_LAS unsigned*)(lds + (bufoff) + ldsw + _i * 8192), 16, 0, 0); } while (0)
; #define PG8_LDA(dst, b, h) do { _Pragma("unroll") for (int m = 0; m < 4; ++m) _Pragma("unroll") for (int k = 0; k < 2; ++k) dst[m][k] = *(const PG8_LAS bf16x8*)(lds + PG8_SA(b, h) + aoff + m * 2048 + k * 1024); } while (0)
; #define PG8_LDB(dst, b, h) do { _Pragma("unroll") for (int n = 0; n < 2; ++n) _Pragma("unroll") for (int k = 0; k < 2; ++k) dst[n][k] = *(const PG8_LAS bf16x8*)(lds + PG8_SB(b, h) + boff + n * 2048 + k * 1024); } while (0)
; #define PG8_WAIT_V(n) asm volatile("s_waitcnt vmcnt(" #n ")" ::: "memory")
; #define PG8_WAIT_L(n) asm volatile("s_waitcnt lgkmcnt(" #n ")" ::: "memory")
; template <class Epi, class Sched, bool ALIGN_EPI = false, bool SP2 = false>
; __device__ __forceinline__ void gemm_phase(PG8_LAS unsigned char* lds, const Gemm g, const Sched& S, const Epi& E) {
;     ...
;         const char* nA = has_next ? (const char*)g.A + (size_t)nxt.pm * tstep + (size_t)nxt.kt0 * kstep : cA; const char* nB = has_next ? (const char*)g.Bt + (size_t)nxt.pn * tstep + (size_t)nxt.kt0 * kstep : cB;
;         const int ntc = cur.ntu;
;         for (int t = 0; t < ntc; t += 2) {
;             if constexpr (Epi::MID) { if (ntc == nt && t == (nt >> 1)) E.mid(acc, cur, wr, wc, fr, fq); }
;             const bool last = (t == ntc - 2);
;             const char* a1 = cA + (size_t)(t + 1) * kstep;
;             const char* a2 = last ? nA : cA + (size_t)(t + 2) * kstep; const char* b2 = last ? nB : cB + (size_t)(t + 2) * kstep;
;             const char* a3 = a2 + kstep; const char* b3 = b2 + kstep;
;             if (last && has_next) S.a_ready(nxt);
;             if constexpr (SP2) {
;             PG8_LDB(B0, 0, 0); PG8_LDB(B1, 0, 1); PG8_SCHED; PG8_LDA(At, 0, 0); PG8_STAGE(PG8_SA(1, 1), a1 + hstep, voffA);
;             PG8_WAIT_V(8); PG8_WAIT_L(0); PG8_BAR; PG8_MMA(0, 0, At, B0); PG8_MMA(0, 1, At, B1); PG8_BAR; PG8_SCHED;
;             PG8_LDA(At, 0, 1); PG8_STAGE(PG8_SB(0, 0), b2, voffB); PG8_STAGE(PG8_SB(0, 1), b2 + hstep, voffB); PG8_STAGE(PG8_SA(0, 0), a2, voffA);
;             PG8_WAIT_V(8); PG8_WAIT_L(0); PG8_BAR; PG8_MMA(1, 0, At, B0); PG8_MMA(1, 1, At, B1); PG8_BAR; PG8_SCHED;
.LBB0_2650:
	ds_read_b128 v[10:13], v195
	ds_read_b128 v[14:17], v195 offset:1024
	ds_read_b128 v[42:45], v195 offset:2048
	ds_read_b128 v[46:49], v195 offset:3072
	ds_read_b128 v[50:53], v238
	ds_read_b128 v[54:57], v238 offset:1024
	ds_read_b128 v[58:61], v238 offset:2048
	ds_read_b128 v[62:65], v238 offset:3072
	s_add_u32 s88, s86, 0xfff00080
	s_addc_u32 s89, s87, -1
	s_cmp_eq_u32 s93, 60
	s_cselect_b32 s91, s19, s89
	s_cselect_b32 s90, s69, s88
	s_cselect_b32 s89, s77, s92
	s_cselect_b32 s88, s79, s85
	s_add_i32 m0, s62, 0xc000
	ds_read_b128 v[66:69], v239
	ds_read_b128 v[70:73], v239 offset:1024
	ds_read_b128 v[170:173], v239 offset:2048
	ds_read_b128 v[174:177], v239 offset:3072
	ds_read_b128 v[178:181], v239 offset:4096
	ds_read_b128 v[208:211], v239 offset:5120
	ds_read_b128 v[212:215], v239 offset:6144
	ds_read_b128 v[216:219], v239 offset:7168
	global_load_lds_dwordx4 v200, s[86:87]
	s_add_i32 m0, s62, 0xe000
	s_nop 0
	global_load_lds_dwordx4 v202, s[86:87]
	s_nop 0
	s_waitcnt vmcnt(8)
	s_waitcnt lgkmcnt(0)
	s_barrier
	s_waitcnt lgkmcnt(0)
	v_mfma_f32_16x16x32_bf16 v[6:9], v[10:13], v[66:69], v[6:9]
	v_mfma_f32_16x16x32_bf16 v[6:9], v[14:17], v[70:73], v[6:9]
	v_mfma_f32_16x16x32_bf16 v[2:5], v[42:45], v[66:69], v[2:5]
	v_mfma_f32_16x16x32_bf16 v[2:5], v[46:49], v[70:73], v[2:5]
	v_mfma_f32_16x16x32_bf16 v[158:161], v[10:13], v[170:173], v[158:161]
	v_mfma_f32_16x16x32_bf16 v[158:161], v[14:17], v[174:177], v[158:161]
	v_mfma_f32_16x16x32_bf16 v[154:157], v[42:45], v[170:173], v[154:157]
	v_mfma_f32_16x16x32_bf16 v[154:157], v[46:49], v[174:177], v[154:157]
	v_mfma_f32_16x16x32_bf16 v[142:145], v[10:13], v[178:181], v[142:145]
	v_mfma_f32_16x16x32_bf16 v[142:145], v[14:17], v[208:211], v[142:145]
	v_mfma_f32_16x16x32_bf16 v[138:141], v[42:45], v[178:181], v[138:141]
	v_mfma_f32_16x16x32_bf16 v[138:141], v[46:49], v[208:211], v[138:141]
	v_mfma_f32_16x16x32_bf16 v[126:129], v[10:13], v[212:215], v[126:129]
	v_mfma_f32_16x16x32_bf16 v[126:129], v[14:17], v[216:219], v[126:129]
	v_mfma_f32_16x16x32_bf16 v[122:125], v[42:45], v[212:215], v[122:125]
	v_mfma_f32_16x16x32_bf16 v[122:125], v[46:49], v[216:219], v[122:125]
	v_mfma_f32_16x16x32_bf16 v[166:169], v[50:53], v[66:69], v[166:169]
	v_mfma_f32_16x16x32_bf16 v[166:169], v[54:57], v[70:73], v[166:169]
	v_mfma_f32_16x16x32_bf16 v[66:69], v[58:61], v[66:69], v[162:165]
	v_mfma_f32_16x16x32_bf16 v[66:69], v[62:65], v[70:73], v[66:69]
	v_mfma_f32_16x16x32_bf16 v[146:149], v[58:61], v[170:173], v[146:149]
	v_mfma_f32_16x16x32_bf16 v[146:149], v[62:65], v[174:177], v[146:149]
	v_mfma_f32_16x16x32_bf16 v[134:137], v[50:53], v[178:181], v[134:137]
	v_mfma_f32_16x16x32_bf16 v[134:137], v[54:57], v[208:211], v[134:137]
	v_mfma_f32_16x16x32_bf16 v[130:133], v[58:61], v[178:181], v[130:133]
	v_mfma_f32_16x16x32_bf16 v[130:133], v[62:65], v[208:211], v[130:133]
	v_mfma_f32_16x16x32_bf16 v[118:121], v[50:53], v[212:215], v[118:121]
	v_mfma_f32_16x16x32_bf16 v[118:121], v[54:57], v[216:219], v[118:121]
	v_mfma_f32_16x16x32_bf16 v[114:117], v[58:61], v[212:215], v[114:117]
	v_mfma_f32_16x16x32_bf16 v[114:117], v[62:65], v[216:219], v[114:117]
	v_mfma_f32_16x16x32_bf16 v[70:73], v[50:53], v[170:173], v[150:153]
	v_mfma_f32_16x16x32_bf16 v[70:73], v[54:57], v[174:177], v[70:73]
	s_barrier
	s_add_i32 vcc_lo, s96, s61
	s_mov_b32 m0, vcc_lo
	ds_read_b128 v[150:153], v239 offset:16384
	ds_read_b128 v[162:165], v239 offset:17408
	ds_read_b128 v[170:173], v239 offset:18432
	ds_read_b128 v[174:177], v239 offset:19456
	ds_read_b128 v[178:181], v239 offset:20480
	ds_read_b128 v[208:211], v239 offset:21504
	ds_read_b128 v[212:215], v239 offset:22528
	ds_read_b128 v[216:219], v239 offset:23552
	global_load_lds_dwordx4 v186, s[88:89]
	s_add_i32 m0, vcc_lo, 0x2000
	s_add_u32 vcc_lo, s88, 0x100000
	s_addc_u32 vcc_hi, s89, 0
	s_add_i32 s58, s70, s61
	global_load_lds_dwordx4 v190, s[88:89]
	s_mov_b32 m0, s58
	s_nop 0
	global_load_lds_dwordx4 v186, vcc
	s_add_i32 m0, s58, 0x2000
	s_nop 0
	global_load_lds_dwordx4 v190, vcc
	s_mov_b32 m0, s62
	s_nop 0
	global_load_lds_dwordx4 v184, s[90:91]
	s_mov_b32 m0, s63
	s_nop 0
	global_load_lds_dwordx4 v188, s[90:91]
	s_waitcnt vmcnt(8)
	s_waitcnt lgkmcnt(0)
	s_barrier
	s_waitcnt lgkmcnt(0)
	v_mfma_f32_16x16x32_bf16 v[110:113], v[10:13], v[150:153], v[110:113]
	v_mfma_f32_16x16x32_bf16 v[110:113], v[14:17], v[162:165], v[110:113]
	v_mfma_f32_16x16x32_bf16 v[106:109], v[42:45], v[150:153], v[106:109]
	v_mfma_f32_16x16x32_bf16 v[106:109], v[46:49], v[162:165], v[106:109]
	v_mfma_f32_16x16x32_bf16 v[94:97], v[10:13], v[170:173], v[94:97]
	v_mfma_f32_16x16x32_bf16 v[94:97], v[14:17], v[174:177], v[94:97]
	v_mfma_f32_16x16x32_bf16 v[90:93], v[42:45], v[170:173], v[90:93]
	v_mfma_f32_16x16x32_bf16 v[90:93], v[46:49], v[174:177], v[90:93]
	v_mfma_f32_16x16x32_bf16 v[78:81], v[10:13], v[178:181], v[78:81]
	v_mfma_f32_16x16x32_bf16 v[78:81], v[14:17], v[208:211], v[78:81]
	v_mfma_f32_16x16x32_bf16 v[74:77], v[42:45], v[178:181], v[74:77]
	v_mfma_f32_16x16x32_bf16 v[74:77], v[46:49], v[208:211], v[74:77]
	v_mfma_f32_16x16x32_bf16 v[10:13], v[10:13], v[212:215], v[30:33]
	v_mfma_f32_16x16x32_bf16 v[10:13], v[14:17], v[216:219], v[10:13]
	v_mfma_f32_16x16x32_bf16 v[14:17], v[42:45], v[212:215], v[26:29]
	v_mfma_f32_16x16x32_bf16 v[14:17], v[46:49], v[216:219], v[14:17]
	v_mfma_f32_16x16x32_bf16 v[26:29], v[50:53], v[150:153], v[102:105]
	v_mfma_f32_16x16x32_bf16 v[42:45], v[54:57], v[162:165], v[26:29]
	v_mfma_f32_16x16x32_bf16 v[26:29], v[58:61], v[150:153], v[98:101]
	v_mfma_f32_16x16x32_bf16 v[46:49], v[62:65], v[162:165], v[26:29]
	v_mfma_f32_16x16x32_bf16 v[26:29], v[50:53], v[170:173], v[86:89]
	v_mfma_f32_16x16x32_bf16 v[86:89], v[54:57], v[174:177], v[26:29]
	v_mfma_f32_16x16x32_bf16 v[26:29], v[58:61], v[170:173], v[82:85]
	v_mfma_f32_16x16x32_bf16 v[82:85], v[62:65], v[174:177], v[26:29]
	v_mfma_f32_16x16x32_bf16 v[26:29], v[50:53], v[178:181], v[38:41]
	v_mfma_f32_16x16x32_bf16 v[38:41], v[54:57], v[208:211], v[26:29]
	v_mfma_f32_16x16x32_bf16 v[26:29], v[58:61], v[178:181], v[34:37]
	v_mfma_f32_16x16x32_bf16 v[34:37], v[62:65], v[208:211], v[26:29]
	v_mfma_f32_16x16x32_bf16 v[22:25], v[50:53], v[212:215], v[22:25]
	v_mfma_f32_16x16x32_bf16 v[22:25], v[54:57], v[216:219], v[22:25]
	v_mfma_f32_16x16x32_bf16 v[18:21], v[58:61], v[212:215], v[18:21]
	v_mfma_f32_16x16x32_bf16 v[18:21], v[62:65], v[216:219], v[18:21]
	s_barrier
; #define PG8_STAGE(bufoff, gbase, voff) do { _Pragma("unroll") for (int _i = 0; _i < 2; ++_i) \
;         __builtin_amdgcn_global_load_lds((const unsigned*)((const char*)(gbase) + (voff)[_i]), (PG8_LAS unsigned*)(lds + (bufoff) + ldsw + _i * 8192), 16, 0, 0); } while (0)
; #define PG8_LDA(dst, b, h) do { _Pragma("unroll") for (int m = 0; m < 4; ++m) _Pragma("unroll") for (int k = 0; k < 2; ++k) dst[m][k] = *(const PG8_LAS bf16x8*)(lds + PG8_SA(b, h) + aoff + m * 2048 + k * 1024); } while (0)
; #define PG8_LDB(dst, b, h) do { _Pragma("unroll") for (int n = 0; n < 2; ++n) _Pragma("unroll") for (int k = 0; k < 2; ++k) dst[n][k] = *(const PG8_LAS bf16x8*)(lds + PG8_SB(b, h) + boff + n * 2048 + k * 1024); } while (0)
; #define PG8_MMA(ai, bj, At, Bt) do { __builtin_amdgcn_s_setprio(1); _Pragma("unroll") for (int m = 0; m < 4; ++m) _Pragma("unroll") for (int n = 0; n < 2; ++n) _Pragma("unroll") for (int k = 0; k < 2; ++k) \
;         acc[ai][bj][m][n] = __builtin_amdgcn_mfma_f32_16x16x32_bf16(Bt[n][k], At[m][k], acc[ai][bj][m][n], 0, 0, 0); __builtin_amdgcn_s_setprio(0); } while (0)
; #define PG8_WAIT_V(n) asm volatile("s_waitcnt vmcnt(" #n ")" ::: "memory")
; #define PG8_WAIT_L(n) asm volatile("s_waitcnt lgkmcnt(" #n ")" ::: "memory")
; #define PG8_BAR __builtin_amdgcn_s_barrier()
; #define PG8_SCHED __builtin_amdgcn_sched_barrier(0)
; template <class Epi, class Sched, bool ALIGN_EPI = false, bool SP2 = false>
; __device__ __forceinline__ void gemm_phase(PG8_LAS unsigned char* lds, const Gemm g, const Sched& S, const Epi& E) {
;     ...
;         for (int t = 0; t < ntc; t += 2) {
;             if constexpr (Epi::MID) { if (ntc == nt && t == (nt >> 1)) E.mid(acc, cur, wr, wc, fr, fq); }
;             const bool last = (t == ntc - 2);
;     ...
;             PG8_LDB(B0, 1, 0); PG8_LDB(B1, 1, 1); PG8_SCHED; PG8_LDA(At, 1, 0); PG8_STAGE(PG8_SA(0, 1), a2 + hstep, voffA);
;             PG8_WAIT_V(8); PG8_WAIT_L(0); PG8_BAR; PG8_MMA(0, 0, At, B0); PG8_MMA(0, 1, At, B1); PG8_BAR; PG8_SCHED;
;             PG8_LDA(At, 1, 1); PG8_STAGE(PG8_SB(1, 0), b3, voffB); PG8_STAGE(PG8_SB(1, 1), b3 + hstep, voffB); PG8_STAGE(PG8_SA(1, 0), a3, voffA);
;             PG8_WAIT_V(8); PG8_WAIT_L(0); PG8_BAR; PG8_MMA(1, 0, At, B0); PG8_MMA(1, 1, At, B1); PG8_BAR; PG8_SCHED;
	s_add_i32 s58, 0, 0x18000
	s_add_i32 s59, 0, 0x1c000
	v_add_u32_e32 v54, s58, v1
	v_add_u32_e32 v98, s59, v1
	ds_read_b128 v[26:29], v54
	ds_read_b128 v[30:33], v54 offset:1024
	ds_read_b128 v[50:53], v54 offset:2048
	ds_read_b128 v[54:57], v54 offset:3072
	ds_read_b128 v[58:61], v98
	ds_read_b128 v[62:65], v98 offset:1024
	ds_read_b128 v[170:173], v98 offset:2048
	ds_read_b128 v[174:177], v98 offset:3072
	s_add_u32 s90, s90, 0x100000
	s_addc_u32 s91, s91, 0
	s_mov_b32 m0, s73
	ds_read_b128 v[98:101], v239 offset:32768
	ds_read_b128 v[102:105], v239 offset:33792
	ds_read_b128 v[178:181], v239 offset:34816
	ds_read_b128 v[208:211], v239 offset:35840
	ds_read_b128 v[212:215], v239 offset:36864
	ds_read_b128 v[216:219], v239 offset:37888
	ds_read_b128 v[220:223], v239 offset:38912
	ds_read_b128 v[224:227], v239 offset:39936
	global_load_lds_dwordx4 v184, s[90:91]
	s_mov_b32 m0, s75
	s_nop 0
	global_load_lds_dwordx4 v188, s[90:91]
	s_nop 0
	s_waitcnt vmcnt(8)
	s_waitcnt lgkmcnt(0)
	s_barrier
	s_waitcnt lgkmcnt(0)
	v_mfma_f32_16x16x32_bf16 v[150:153], v[26:29], v[178:181], v[158:161]
	v_mfma_f32_16x16x32_bf16 v[158:161], v[30:33], v[208:211], v[150:153]
	v_mfma_f32_16x16x32_bf16 v[6:9], v[26:29], v[98:101], v[6:9]
	v_mfma_f32_16x16x32_bf16 v[6:9], v[30:33], v[102:105], v[6:9]
	v_mfma_f32_16x16x32_bf16 v[2:5], v[50:53], v[98:101], v[2:5]
	v_mfma_f32_16x16x32_bf16 v[2:5], v[54:57], v[102:105], v[2:5]
	v_mfma_f32_16x16x32_bf16 v[150:153], v[50:53], v[178:181], v[154:157]
	v_mfma_f32_16x16x32_bf16 v[154:157], v[54:57], v[208:211], v[150:153]
	v_mfma_f32_16x16x32_bf16 v[142:145], v[26:29], v[212:215], v[142:145]
	v_mfma_f32_16x16x32_bf16 v[142:145], v[30:33], v[216:219], v[142:145]
	v_mfma_f32_16x16x32_bf16 v[138:141], v[50:53], v[212:215], v[138:141]
	v_mfma_f32_16x16x32_bf16 v[138:141], v[54:57], v[216:219], v[138:141]
	v_mfma_f32_16x16x32_bf16 v[126:129], v[26:29], v[220:223], v[126:129]
	v_mfma_f32_16x16x32_bf16 v[126:129], v[30:33], v[224:227], v[126:129]
	v_mfma_f32_16x16x32_bf16 v[122:125], v[50:53], v[220:223], v[122:125]
	v_mfma_f32_16x16x32_bf16 v[122:125], v[54:57], v[224:227], v[122:125]
	v_mfma_f32_16x16x32_bf16 v[66:69], v[170:173], v[98:101], v[66:69]
	v_mfma_f32_16x16x32_bf16 v[162:165], v[174:177], v[102:105], v[66:69]
	v_mfma_f32_16x16x32_bf16 v[150:153], v[58:61], v[98:101], v[166:169]
	v_mfma_f32_16x16x32_bf16 v[166:169], v[62:65], v[102:105], v[150:153]
	v_mfma_f32_16x16x32_bf16 v[66:69], v[58:61], v[178:181], v[70:73]
	v_mfma_f32_16x16x32_bf16 v[150:153], v[62:65], v[208:211], v[66:69]
	v_mfma_f32_16x16x32_bf16 v[66:69], v[170:173], v[178:181], v[146:149]
	v_mfma_f32_16x16x32_bf16 v[146:149], v[174:177], v[208:211], v[66:69]
	v_mfma_f32_16x16x32_bf16 v[66:69], v[58:61], v[212:215], v[134:137]
	v_mfma_f32_16x16x32_bf16 v[134:137], v[62:65], v[216:219], v[66:69]
	v_mfma_f32_16x16x32_bf16 v[66:69], v[170:173], v[212:215], v[130:133]
	v_mfma_f32_16x16x32_bf16 v[130:133], v[174:177], v[216:219], v[66:69]
	v_mfma_f32_16x16x32_bf16 v[66:69], v[58:61], v[220:223], v[118:121]
	v_mfma_f32_16x16x32_bf16 v[118:121], v[62:65], v[224:227], v[66:69]
	v_mfma_f32_16x16x32_bf16 v[66:69], v[170:173], v[220:223], v[114:117]
	v_mfma_f32_16x16x32_bf16 v[114:117], v[174:177], v[224:227], v[66:69]
	s_barrier
	s_add_i32 s58, s58, s61
	s_add_u32 s100, s88, 0x80
	s_addc_u32 s101, s89, 0
	s_mov_b32 m0, s58
	s_nop 1
	ds_read_b128 v[66:69], v239 offset:49152
	ds_read_b128 v[70:73], v239 offset:50176
	ds_read_b128 v[178:181], v239 offset:51200
	ds_read_b128 v[208:211], v239 offset:52224
	ds_read_b128 v[212:215], v239 offset:53248
	ds_read_b128 v[216:219], v239 offset:54272
	ds_read_b128 v[220:223], v239 offset:55296
	ds_read_b128 v[224:227], v239 offset:56320
	global_load_lds_dwordx4 v186, s[100:101]
	s_add_i32 m0, s58, 0x2000
	s_add_i32 s58, s59, s61
	global_load_lds_dwordx4 v190, s[100:101]
	s_add_u32 s88, s88, 0x100080
	s_addc_u32 s89, s89, 0
	s_add_u32 s100, s90, 0xfff00080
	s_addc_u32 s101, s91, -1
	s_mov_b32 m0, s58
	s_nop 0
	global_load_lds_dwordx4 v186, s[88:89]
	s_add_i32 m0, s58, 0x2000
	s_nop 0
	global_load_lds_dwordx4 v190, s[88:89]
	s_mov_b32 m0, s29
	s_nop 0
	global_load_lds_dwordx4 v184, s[100:101]
	s_mov_b32 m0, s95
	s_nop 0
	global_load_lds_dwordx4 v188, s[100:101]
	s_nop 0
	s_waitcnt vmcnt(8)
	s_waitcnt lgkmcnt(0)
	s_barrier
	s_waitcnt lgkmcnt(0)
	v_mfma_f32_16x16x32_bf16 v[98:101], v[26:29], v[66:69], v[110:113]
	v_mfma_f32_16x16x32_bf16 v[110:113], v[30:33], v[70:73], v[98:101]
	v_mfma_f32_16x16x32_bf16 v[94:97], v[26:29], v[178:181], v[94:97]
	v_mfma_f32_16x16x32_bf16 v[94:97], v[30:33], v[208:211], v[94:97]
	v_mfma_f32_16x16x32_bf16 v[78:81], v[26:29], v[212:215], v[78:81]
	v_mfma_f32_16x16x32_bf16 v[78:81], v[30:33], v[216:219], v[78:81]
	v_mfma_f32_16x16x32_bf16 v[10:13], v[26:29], v[220:223], v[10:13]
	v_mfma_f32_16x16x32_bf16 v[30:33], v[30:33], v[224:227], v[10:13]
	v_mfma_f32_16x16x32_bf16 v[98:101], v[50:53], v[66:69], v[106:109]
	v_mfma_f32_16x16x32_bf16 v[106:109], v[54:57], v[70:73], v[98:101]
	v_mfma_f32_16x16x32_bf16 v[90:93], v[50:53], v[178:181], v[90:93]
	v_mfma_f32_16x16x32_bf16 v[90:93], v[54:57], v[208:211], v[90:93]
	v_mfma_f32_16x16x32_bf16 v[74:77], v[50:53], v[212:215], v[74:77]
	v_mfma_f32_16x16x32_bf16 v[74:77], v[54:57], v[216:219], v[74:77]
	v_mfma_f32_16x16x32_bf16 v[10:13], v[50:53], v[220:223], v[14:17]
	v_mfma_f32_16x16x32_bf16 v[26:29], v[54:57], v[224:227], v[10:13]
	v_mfma_f32_16x16x32_bf16 v[10:13], v[58:61], v[66:69], v[42:45]
	v_mfma_f32_16x16x32_bf16 v[102:105], v[62:65], v[70:73], v[10:13]
	v_mfma_f32_16x16x32_bf16 v[10:13], v[170:173], v[66:69], v[46:49]
	v_mfma_f32_16x16x32_bf16 v[98:101], v[174:177], v[70:73], v[10:13]
	v_mfma_f32_16x16x32_bf16 v[10:13], v[58:61], v[178:181], v[86:89]
	v_mfma_f32_16x16x32_bf16 v[86:89], v[62:65], v[208:211], v[10:13]
	v_mfma_f32_16x16x32_bf16 v[10:13], v[170:173], v[178:181], v[82:85]
	v_mfma_f32_16x16x32_bf16 v[82:85], v[174:177], v[208:211], v[10:13]
	v_mfma_f32_16x16x32_bf16 v[10:13], v[58:61], v[212:215], v[38:41]
	v_mfma_f32_16x16x32_bf16 v[38:41], v[62:65], v[216:219], v[10:13]
	v_mfma_f32_16x16x32_bf16 v[10:13], v[170:173], v[212:215], v[34:37]
	v_mfma_f32_16x16x32_bf16 v[34:37], v[174:177], v[216:219], v[10:13]
	v_mfma_f32_16x16x32_bf16 v[10:13], v[58:61], v[220:223], v[22:25]
	v_mfma_f32_16x16x32_bf16 v[22:25], v[62:65], v[224:227], v[10:13]
	v_mfma_f32_16x16x32_bf16 v[10:13], v[170:173], v[220:223], v[18:21]
	v_mfma_f32_16x16x32_bf16 v[18:21], v[174:177], v[224:227], v[10:13]
	s_barrier
	s_add_i32 s93, s93, 2
	s_add_u32 s86, s86, 0x100
	s_addc_u32 s87, s87, 0
	s_add_u32 s85, s85, 0x100
	s_addc_u32 s92, s92, 0
	s_cmp_gt_u32 s93, 61
	s_cbranch_scc0 .LBB0_2650
	s_and_b64 vcc, exec, s[42:43]
	s_cbranch_vccz .LBB0_2653
	s_barrier

; #define PG8_STAGE(bufoff, gbase, voff) do { _Pragma("unroll") for (int _i = 0; _i < 2; ++_i) \
;         __builtin_amdgcn_global_load_lds((const unsigned*)((const char*)(gbase) + (voff)[_i]), (PG8_LAS unsigned*)(lds + (bufoff) + ldsw + _i * 8192), 16, 0, 0); } while (0)
; #define PG8_LDA(dst, b, h) do { _Pragma("unroll") for (int m = 0; m < 4; ++m) _Pragma("unroll") for (int k = 0; k < 2; ++k) dst[m][k] = *(const PG8_LAS bf16x8*)(lds + PG8_SA(b, h) + aoff + m * 2048 + k * 1024); } while (0)
; #define PG8_LDB(dst, b, h) do { _Pragma("unroll") for (int n = 0; n < 2; ++n) _Pragma("unroll") for (int k = 0; k < 2; ++k) dst[n][k] = *(const PG8_LAS bf16x8*)(lds + PG8_SB(b, h) + boff + n * 2048 + k * 1024); } while (0)
; #define PG8_WAIT_V(n) asm volatile("s_waitcnt vmcnt(" #n ")" ::: "memory")
; #define PG8_WAIT_L(n) asm volatile("s_waitcnt lgkmcnt(" #n ")" ::: "memory")
; template <class Epi, class Sched, bool ALIGN_EPI = false, bool SP2 = false>
; __device__ __forceinline__ void gemm_phase(PG8_LAS unsigned char* lds, const Gemm g, const Sched& S, const Epi& E) {
;     ...
;         const char* nA = has_next ? (const char*)g.A + (size_t)nxt.pm * tstep + (size_t)nxt.kt0 * kstep : cA; const char* nB = has_next ? (const char*)g.Bt + (size_t)nxt.pn * tstep + (size_t)nxt.kt0 * kstep : cB;
;         const int ntc = cur.ntu;
;         for (int t = 0; t < ntc; t += 2) {
;             if constexpr (Epi::MID) { if (ntc == nt && t == (nt >> 1)) E.mid(acc, cur, wr, wc, fr, fq); }
;             const bool last = (t == ntc - 2);
;             const char* a1 = cA + (size_t)(t + 1) * kstep;
;             const char* a2 = last ? nA : cA + (size_t)(t + 2) * kstep; const char* b2 = last ? nB : cB + (size_t)(t + 2) * kstep;
;             const char* a3 = a2 + kstep; const char* b3 = b2 + kstep;
;             if (last && has_next) S.a_ready(nxt);
;             if constexpr (SP2) {
;             PG8_LDB(B0, 0, 0); PG8_LDB(B1, 0, 1); PG8_SCHED; PG8_LDA(At, 0, 0); PG8_STAGE(PG8_SA(1, 1), a1 + hstep, voffA);
;             PG8_WAIT_V(8); PG8_WAIT_L(0); PG8_BAR; PG8_MMA(0, 0, At, B0); PG8_MMA(0, 1, At, B1); PG8_BAR; PG8_SCHED;
;             PG8_LDA(At, 0, 1); PG8_STAGE(PG8_SB(0, 0), b2, voffB); PG8_STAGE(PG8_SB(0, 1), b2 + hstep, voffB); PG8_STAGE(PG8_SA(0, 0), a2, voffA);
;             PG8_WAIT_V(8); PG8_WAIT_L(0); PG8_BAR; PG8_MMA(1, 0, At, B0); PG8_MMA(1, 1, At, B1); PG8_BAR; PG8_SCHED;
.LBB0_3522:
	ds_read_b128 v[144:147], v177
	ds_read_b128 v[148:151], v177 offset:1024
	ds_read_b128 v[152:155], v177 offset:2048
	ds_read_b128 v[156:159], v177 offset:3072
	ds_read_b128 v[160:163], v178
	ds_read_b128 v[164:167], v178 offset:1024
	ds_read_b128 v[168:171], v178 offset:2048
	ds_read_b128 v[172:175], v178 offset:3072
	s_add_u32 s40, s38, 0x100
	s_addc_u32 s41, s39, 0
	s_cmp_eq_u32 s69, s71
	s_cselect_b32 s45, s35, s41
	s_cselect_b32 s44, s34, s40
	s_cselect_b32 s43, s37, s70
	s_cselect_b32 s42, s36, s31
	s_add_i32 m0, s51, 0xc000
	ds_read_b128 v[180:183], v179
	ds_read_b128 v[184:187], v179 offset:1024
	ds_read_b128 v[188:191], v179 offset:2048
	ds_read_b128 v[192:195], v179 offset:3072
	ds_read_b128 v[196:199], v179 offset:4096
	ds_read_b128 v[200:203], v179 offset:5120
	ds_read_b128 v[204:207], v179 offset:6144
	ds_read_b128 v[208:211], v179 offset:7168
	global_load_lds_dwordx4 v138, s[38:39]
	s_add_i32 m0, s51, 0xe000
	s_nop 0
	global_load_lds_dwordx4 v140, s[38:39]
	s_waitcnt vmcnt(8)
	s_waitcnt lgkmcnt(0)
	s_barrier
	s_waitcnt lgkmcnt(0)
	v_mfma_f32_16x16x32_bf16 v[126:129], v[144:147], v[180:183], v[126:129]
	v_mfma_f32_16x16x32_bf16 v[126:129], v[148:151], v[184:187], v[126:129]
	v_mfma_f32_16x16x32_bf16 v[122:125], v[152:155], v[180:183], v[122:125]
	v_mfma_f32_16x16x32_bf16 v[122:125], v[156:159], v[184:187], v[122:125]
	v_mfma_f32_16x16x32_bf16 v[110:113], v[144:147], v[188:191], v[110:113]
	v_mfma_f32_16x16x32_bf16 v[110:113], v[148:151], v[192:195], v[110:113]
	v_mfma_f32_16x16x32_bf16 v[106:109], v[152:155], v[188:191], v[106:109]
	v_mfma_f32_16x16x32_bf16 v[106:109], v[156:159], v[192:195], v[106:109]
	v_mfma_f32_16x16x32_bf16 v[94:97], v[144:147], v[196:199], v[94:97]
	v_mfma_f32_16x16x32_bf16 v[94:97], v[148:151], v[200:203], v[94:97]
	v_mfma_f32_16x16x32_bf16 v[90:93], v[152:155], v[196:199], v[90:93]
	v_mfma_f32_16x16x32_bf16 v[90:93], v[156:159], v[200:203], v[90:93]
	v_mfma_f32_16x16x32_bf16 v[78:81], v[144:147], v[204:207], v[78:81]
	v_mfma_f32_16x16x32_bf16 v[78:81], v[148:151], v[208:211], v[78:81]
	v_mfma_f32_16x16x32_bf16 v[74:77], v[152:155], v[204:207], v[74:77]
	v_mfma_f32_16x16x32_bf16 v[74:77], v[156:159], v[208:211], v[74:77]
	v_mfma_f32_16x16x32_bf16 v[118:121], v[160:163], v[180:183], v[118:121]
	v_mfma_f32_16x16x32_bf16 v[118:121], v[164:167], v[184:187], v[118:121]
	v_mfma_f32_16x16x32_bf16 v[114:117], v[168:171], v[180:183], v[114:117]
	v_mfma_f32_16x16x32_bf16 v[114:117], v[172:175], v[184:187], v[114:117]
	v_mfma_f32_16x16x32_bf16 v[102:105], v[160:163], v[188:191], v[102:105]
	v_mfma_f32_16x16x32_bf16 v[102:105], v[164:167], v[192:195], v[102:105]
	v_mfma_f32_16x16x32_bf16 v[98:101], v[168:171], v[188:191], v[98:101]
	v_mfma_f32_16x16x32_bf16 v[98:101], v[172:175], v[192:195], v[98:101]
	v_mfma_f32_16x16x32_bf16 v[86:89], v[160:163], v[196:199], v[86:89]
	v_mfma_f32_16x16x32_bf16 v[86:89], v[164:167], v[200:203], v[86:89]
	v_mfma_f32_16x16x32_bf16 v[82:85], v[168:171], v[196:199], v[82:85]
	v_mfma_f32_16x16x32_bf16 v[82:85], v[172:175], v[200:203], v[82:85]
	v_mfma_f32_16x16x32_bf16 v[70:73], v[160:163], v[204:207], v[70:73]
	v_mfma_f32_16x16x32_bf16 v[70:73], v[164:167], v[208:211], v[70:73]
	v_mfma_f32_16x16x32_bf16 v[66:69], v[168:171], v[204:207], v[66:69]
	v_mfma_f32_16x16x32_bf16 v[66:69], v[172:175], v[208:211], v[66:69]
	s_barrier
	s_add_i32 s38, s63, s50
	s_mov_b32 m0, s38
	ds_read_b128 v[180:183], v179 offset:16384
	ds_read_b128 v[184:187], v179 offset:17408
	ds_read_b128 v[188:191], v179 offset:18432
	ds_read_b128 v[192:195], v179 offset:19456
	ds_read_b128 v[196:199], v179 offset:20480
	ds_read_b128 v[200:203], v179 offset:21504
	ds_read_b128 v[204:207], v179 offset:22528
	ds_read_b128 v[208:211], v179 offset:23552
	global_load_lds_dwordx4 v130, s[42:43]
	s_add_i32 m0, s38, 0x2000
	s_add_u32 s38, s42, 0x300000
	s_addc_u32 s39, s43, 0
	s_add_i32 s58, s64, s50
	global_load_lds_dwordx4 v132, s[42:43]
	s_mov_b32 m0, s58
	s_nop 0
	global_load_lds_dwordx4 v130, s[38:39]
	s_add_i32 m0, s58, 0x2000
	s_nop 0
	global_load_lds_dwordx4 v132, s[38:39]
	s_mov_b32 m0, s51
	s_nop 0
	global_load_lds_dwordx4 v130, s[44:45]
	s_mov_b32 m0, s52
	s_nop 0
	global_load_lds_dwordx4 v132, s[44:45]
	s_waitcnt vmcnt(8)
	s_waitcnt lgkmcnt(0)
	s_barrier
	s_waitcnt lgkmcnt(0)
	v_mfma_f32_16x16x32_bf16 v[62:65], v[144:147], v[180:183], v[62:65]
	v_mfma_f32_16x16x32_bf16 v[62:65], v[148:151], v[184:187], v[62:65]
	v_mfma_f32_16x16x32_bf16 v[58:61], v[152:155], v[180:183], v[58:61]
	v_mfma_f32_16x16x32_bf16 v[58:61], v[156:159], v[184:187], v[58:61]
	v_mfma_f32_16x16x32_bf16 v[46:49], v[144:147], v[188:191], v[46:49]
	v_mfma_f32_16x16x32_bf16 v[46:49], v[148:151], v[192:195], v[46:49]
	v_mfma_f32_16x16x32_bf16 v[42:45], v[152:155], v[188:191], v[42:45]
	v_mfma_f32_16x16x32_bf16 v[42:45], v[156:159], v[192:195], v[42:45]
	v_mfma_f32_16x16x32_bf16 v[30:33], v[144:147], v[196:199], v[30:33]
	v_mfma_f32_16x16x32_bf16 v[30:33], v[148:151], v[200:203], v[30:33]
	v_mfma_f32_16x16x32_bf16 v[26:29], v[152:155], v[196:199], v[26:29]
	v_mfma_f32_16x16x32_bf16 v[26:29], v[156:159], v[200:203], v[26:29]
	v_mfma_f32_16x16x32_bf16 v[14:17], v[144:147], v[204:207], v[14:17]
	v_mfma_f32_16x16x32_bf16 v[14:17], v[148:151], v[208:211], v[14:17]
	v_mfma_f32_16x16x32_bf16 v[10:13], v[152:155], v[204:207], v[10:13]
	v_mfma_f32_16x16x32_bf16 v[10:13], v[156:159], v[208:211], v[10:13]
	v_mfma_f32_16x16x32_bf16 v[54:57], v[160:163], v[180:183], v[54:57]
	v_mfma_f32_16x16x32_bf16 v[54:57], v[164:167], v[184:187], v[54:57]
	v_mfma_f32_16x16x32_bf16 v[50:53], v[168:171], v[180:183], v[50:53]
	v_mfma_f32_16x16x32_bf16 v[50:53], v[172:175], v[184:187], v[50:53]
	v_mfma_f32_16x16x32_bf16 v[38:41], v[160:163], v[188:191], v[38:41]
	v_mfma_f32_16x16x32_bf16 v[38:41], v[164:167], v[192:195], v[38:41]
	v_mfma_f32_16x16x32_bf16 v[34:37], v[168:171], v[188:191], v[34:37]
	v_mfma_f32_16x16x32_bf16 v[34:37], v[172:175], v[192:195], v[34:37]
	v_mfma_f32_16x16x32_bf16 v[22:25], v[160:163], v[196:199], v[22:25]
	v_mfma_f32_16x16x32_bf16 v[22:25], v[164:167], v[200:203], v[22:25]
	v_mfma_f32_16x16x32_bf16 v[18:21], v[168:171], v[196:199], v[18:21]
	v_mfma_f32_16x16x32_bf16 v[18:21], v[172:175], v[200:203], v[18:21]
	v_mfma_f32_16x16x32_bf16 v[6:9], v[160:163], v[204:207], v[6:9]
	v_mfma_f32_16x16x32_bf16 v[6:9], v[164:167], v[208:211], v[6:9]
	v_mfma_f32_16x16x32_bf16 v[2:5], v[168:171], v[204:207], v[2:5]
	v_mfma_f32_16x16x32_bf16 v[2:5], v[172:175], v[208:211], v[2:5]
	s_barrier
; #define PG8_STAGE(bufoff, gbase, voff) do { _Pragma("unroll") for (int _i = 0; _i < 2; ++_i) \
;         __builtin_amdgcn_global_load_lds((const unsigned*)((const char*)(gbase) + (voff)[_i]), (PG8_LAS unsigned*)(lds + (bufoff) + ldsw + _i * 8192), 16, 0, 0); } while (0)
; #define PG8_LDA(dst, b, h) do { _Pragma("unroll") for (int m = 0; m < 4; ++m) _Pragma("unroll") for (int k = 0; k < 2; ++k) dst[m][k] = *(const PG8_LAS bf16x8*)(lds + PG8_SA(b, h) + aoff + m * 2048 + k * 1024); } while (0)
; #define PG8_LDB(dst, b, h) do { _Pragma("unroll") for (int n = 0; n < 2; ++n) _Pragma("unroll") for (int k = 0; k < 2; ++k) dst[n][k] = *(const PG8_LAS bf16x8*)(lds + PG8_SB(b, h) + boff + n * 2048 + k * 1024); } while (0)
; #define PG8_MMA(ai, bj, At, Bt) do { __builtin_amdgcn_s_setprio(1); _Pragma("unroll") for (int m = 0; m < 4; ++m) _Pragma("unroll") for (int n = 0; n < 2; ++n) _Pragma("unroll") for (int k = 0; k < 2; ++k) \
;         acc[ai][bj][m][n] = __builtin_amdgcn_mfma_f32_16x16x32_bf16(Bt[n][k], At[m][k], acc[ai][bj][m][n], 0, 0, 0); __builtin_amdgcn_s_setprio(0); } while (0)
; #define PG8_WAIT_V(n) asm volatile("s_waitcnt vmcnt(" #n ")" ::: "memory")
; #define PG8_WAIT_L(n) asm volatile("s_waitcnt lgkmcnt(" #n ")" ::: "memory")
; #define PG8_BAR __builtin_amdgcn_s_barrier()
; #define PG8_SCHED __builtin_amdgcn_sched_barrier(0)
; template <class Epi, class Sched, bool ALIGN_EPI = false, bool SP2 = false>
; __device__ __forceinline__ void gemm_phase(PG8_LAS unsigned char* lds, const Gemm g, const Sched& S, const Epi& E) {
;     ...
;         for (int t = 0; t < ntc; t += 2) {
;             if constexpr (Epi::MID) { if (ntc == nt && t == (nt >> 1)) E.mid(acc, cur, wr, wc, fr, fq); }
;             const bool last = (t == ntc - 2);
;     ...
;             PG8_LDB(B0, 1, 0); PG8_LDB(B1, 1, 1); PG8_SCHED; PG8_LDA(At, 1, 0); PG8_STAGE(PG8_SA(0, 1), a2 + hstep, voffA);
;             PG8_WAIT_V(8); PG8_WAIT_L(0); PG8_BAR; PG8_MMA(0, 0, At, B0); PG8_MMA(0, 1, At, B1); PG8_BAR; PG8_SCHED;
;             PG8_LDA(At, 1, 1); PG8_STAGE(PG8_SB(1, 0), b3, voffB); PG8_STAGE(PG8_SB(1, 1), b3 + hstep, voffB); PG8_STAGE(PG8_SA(1, 0), a3, voffA);
;             PG8_WAIT_V(8); PG8_WAIT_L(0); PG8_BAR; PG8_MMA(1, 0, At, B0); PG8_MMA(1, 1, At, B1); PG8_BAR; PG8_SCHED;
	s_add_i32 s58, 0, 0x18000
	v_add_u32_e32 v134, s58, v1
	s_add_i32 s59, 0, 0x1c000
	ds_read_b128 v[144:147], v134
	ds_read_b128 v[148:151], v134 offset:1024
	ds_read_b128 v[152:155], v134 offset:2048
	ds_read_b128 v[156:159], v134 offset:3072
	v_add_u32_e32 v134, s59, v1
	ds_read_b128 v[160:163], v134
	ds_read_b128 v[164:167], v134 offset:1024
	ds_read_b128 v[168:171], v134 offset:2048
	ds_read_b128 v[172:175], v134 offset:3072
	s_add_u32 s38, s44, 0x300000
	s_addc_u32 s39, s45, 0
	s_mov_b32 m0, s53
	ds_read_b128 v[180:183], v179 offset:32768
	ds_read_b128 v[184:187], v179 offset:33792
	ds_read_b128 v[188:191], v179 offset:34816
	ds_read_b128 v[192:195], v179 offset:35840
	ds_read_b128 v[196:199], v179 offset:36864
	ds_read_b128 v[200:203], v179 offset:37888
	ds_read_b128 v[204:207], v179 offset:38912
	ds_read_b128 v[208:211], v179 offset:39936
	global_load_lds_dwordx4 v130, s[38:39]
	s_mov_b32 m0, s54
	s_nop 0
	global_load_lds_dwordx4 v132, s[38:39]
	s_nop 0
	s_waitcnt vmcnt(8)
	s_waitcnt lgkmcnt(0)
	s_barrier
	s_waitcnt lgkmcnt(0)
	v_mfma_f32_16x16x32_bf16 v[126:129], v[144:147], v[180:183], v[126:129]
	v_mfma_f32_16x16x32_bf16 v[126:129], v[148:151], v[184:187], v[126:129]
	v_mfma_f32_16x16x32_bf16 v[122:125], v[152:155], v[180:183], v[122:125]
	v_mfma_f32_16x16x32_bf16 v[122:125], v[156:159], v[184:187], v[122:125]
	v_mfma_f32_16x16x32_bf16 v[110:113], v[144:147], v[188:191], v[110:113]
	v_mfma_f32_16x16x32_bf16 v[110:113], v[148:151], v[192:195], v[110:113]
	v_mfma_f32_16x16x32_bf16 v[106:109], v[152:155], v[188:191], v[106:109]
	v_mfma_f32_16x16x32_bf16 v[106:109], v[156:159], v[192:195], v[106:109]
	v_mfma_f32_16x16x32_bf16 v[94:97], v[144:147], v[196:199], v[94:97]
	v_mfma_f32_16x16x32_bf16 v[94:97], v[148:151], v[200:203], v[94:97]
	v_mfma_f32_16x16x32_bf16 v[90:93], v[152:155], v[196:199], v[90:93]
	v_mfma_f32_16x16x32_bf16 v[90:93], v[156:159], v[200:203], v[90:93]
	v_mfma_f32_16x16x32_bf16 v[78:81], v[144:147], v[204:207], v[78:81]
	v_mfma_f32_16x16x32_bf16 v[78:81], v[148:151], v[208:211], v[78:81]
	v_mfma_f32_16x16x32_bf16 v[74:77], v[152:155], v[204:207], v[74:77]
	v_mfma_f32_16x16x32_bf16 v[74:77], v[156:159], v[208:211], v[74:77]
	v_mfma_f32_16x16x32_bf16 v[118:121], v[160:163], v[180:183], v[118:121]
	v_mfma_f32_16x16x32_bf16 v[118:121], v[164:167], v[184:187], v[118:121]
	v_mfma_f32_16x16x32_bf16 v[114:117], v[168:171], v[180:183], v[114:117]
	v_mfma_f32_16x16x32_bf16 v[114:117], v[172:175], v[184:187], v[114:117]
	v_mfma_f32_16x16x32_bf16 v[102:105], v[160:163], v[188:191], v[102:105]
	v_mfma_f32_16x16x32_bf16 v[102:105], v[164:167], v[192:195], v[102:105]
	v_mfma_f32_16x16x32_bf16 v[98:101], v[168:171], v[188:191], v[98:101]
	v_mfma_f32_16x16x32_bf16 v[98:101], v[172:175], v[192:195], v[98:101]
	v_mfma_f32_16x16x32_bf16 v[86:89], v[160:163], v[196:199], v[86:89]
	v_mfma_f32_16x16x32_bf16 v[86:89], v[164:167], v[200:203], v[86:89]
	v_mfma_f32_16x16x32_bf16 v[82:85], v[168:171], v[196:199], v[82:85]
	v_mfma_f32_16x16x32_bf16 v[82:85], v[172:175], v[200:203], v[82:85]
	v_mfma_f32_16x16x32_bf16 v[70:73], v[160:163], v[204:207], v[70:73]
	v_mfma_f32_16x16x32_bf16 v[70:73], v[164:167], v[208:211], v[70:73]
	v_mfma_f32_16x16x32_bf16 v[66:69], v[168:171], v[204:207], v[66:69]
	v_mfma_f32_16x16x32_bf16 v[66:69], v[172:175], v[208:211], v[66:69]
	s_barrier
	s_add_i32 s38, s58, s50
	s_add_u32 s98, s42, 0x80
	s_addc_u32 s99, s43, 0
	s_add_u32 s100, s44, 0x80
	s_addc_u32 s101, s45, 0
	s_mov_b32 m0, s38
	ds_read_b128 v[180:183], v179 offset:49152
	ds_read_b128 v[184:187], v179 offset:50176
	ds_read_b128 v[188:191], v179 offset:51200
	ds_read_b128 v[192:195], v179 offset:52224
	ds_read_b128 v[196:199], v179 offset:53248
	ds_read_b128 v[200:203], v179 offset:54272
	ds_read_b128 v[204:207], v179 offset:55296
	ds_read_b128 v[208:211], v179 offset:56320
	global_load_lds_dwordx4 v130, s[98:99]
	s_add_i32 m0, s38, 0x2000
	s_add_u32 s38, s42, 0x300080
	s_addc_u32 s39, s43, 0
	s_add_i32 s42, s59, s50
	global_load_lds_dwordx4 v132, s[98:99]
	s_mov_b32 m0, s42
	s_nop 0
	global_load_lds_dwordx4 v130, s[38:39]
	s_add_i32 m0, s42, 0x2000
	s_nop 0
	global_load_lds_dwordx4 v132, s[38:39]
	s_mov_b32 m0, s57
	s_nop 0
	global_load_lds_dwordx4 v130, s[100:101]
	s_mov_b32 m0, s60
	s_nop 0
	global_load_lds_dwordx4 v132, s[100:101]
	s_waitcnt vmcnt(8)
	s_waitcnt lgkmcnt(0)
	s_barrier
	s_waitcnt lgkmcnt(0)
	v_mfma_f32_16x16x32_bf16 v[62:65], v[144:147], v[180:183], v[62:65]
	v_mfma_f32_16x16x32_bf16 v[62:65], v[148:151], v[184:187], v[62:65]
	v_mfma_f32_16x16x32_bf16 v[58:61], v[152:155], v[180:183], v[58:61]
	v_mfma_f32_16x16x32_bf16 v[58:61], v[156:159], v[184:187], v[58:61]
	v_mfma_f32_16x16x32_bf16 v[46:49], v[144:147], v[188:191], v[46:49]
	v_mfma_f32_16x16x32_bf16 v[46:49], v[148:151], v[192:195], v[46:49]
	v_mfma_f32_16x16x32_bf16 v[42:45], v[152:155], v[188:191], v[42:45]
	v_mfma_f32_16x16x32_bf16 v[42:45], v[156:159], v[192:195], v[42:45]
	v_mfma_f32_16x16x32_bf16 v[30:33], v[144:147], v[196:199], v[30:33]
	v_mfma_f32_16x16x32_bf16 v[30:33], v[148:151], v[200:203], v[30:33]
	v_mfma_f32_16x16x32_bf16 v[26:29], v[152:155], v[196:199], v[26:29]
	v_mfma_f32_16x16x32_bf16 v[26:29], v[156:159], v[200:203], v[26:29]
	v_mfma_f32_16x16x32_bf16 v[14:17], v[144:147], v[204:207], v[14:17]
	v_mfma_f32_16x16x32_bf16 v[14:17], v[148:151], v[208:211], v[14:17]
	v_mfma_f32_16x16x32_bf16 v[10:13], v[152:155], v[204:207], v[10:13]
	v_mfma_f32_16x16x32_bf16 v[10:13], v[156:159], v[208:211], v[10:13]
	v_mfma_f32_16x16x32_bf16 v[54:57], v[160:163], v[180:183], v[54:57]
	v_mfma_f32_16x16x32_bf16 v[54:57], v[164:167], v[184:187], v[54:57]
	v_mfma_f32_16x16x32_bf16 v[50:53], v[168:171], v[180:183], v[50:53]
	v_mfma_f32_16x16x32_bf16 v[50:53], v[172:175], v[184:187], v[50:53]
	v_mfma_f32_16x16x32_bf16 v[38:41], v[160:163], v[188:191], v[38:41]
	v_mfma_f32_16x16x32_bf16 v[38:41], v[164:167], v[192:195], v[38:41]
	v_mfma_f32_16x16x32_bf16 v[34:37], v[168:171], v[188:191], v[34:37]
	v_mfma_f32_16x16x32_bf16 v[34:37], v[172:175], v[192:195], v[34:37]
	v_mfma_f32_16x16x32_bf16 v[22:25], v[160:163], v[196:199], v[22:25]
	v_mfma_f32_16x16x32_bf16 v[22:25], v[164:167], v[200:203], v[22:25]
	v_mfma_f32_16x16x32_bf16 v[18:21], v[168:171], v[196:199], v[18:21]
	v_mfma_f32_16x16x32_bf16 v[18:21], v[172:175], v[200:203], v[18:21]
	v_mfma_f32_16x16x32_bf16 v[6:9], v[160:163], v[204:207], v[6:9]
	v_mfma_f32_16x16x32_bf16 v[6:9], v[164:167], v[208:211], v[6:9]
	v_mfma_f32_16x16x32_bf16 v[2:5], v[168:171], v[204:207], v[2:5]
	v_mfma_f32_16x16x32_bf16 v[2:5], v[172:175], v[208:211], v[2:5]
	s_barrier
	s_add_i32 s42, s71, 2
	s_add_u32 s31, s31, 0x100
	s_addc_u32 s70, s70, 0
	s_cmp_ge_i32 s71, s69
	s_mov_b64 s[38:39], s[40:41]
	s_mov_b32 s71, s42
	s_cbranch_scc0 .LBB0_3522
	s_and_b64 vcc, exec, s[20:21]
	s_cbranch_vccz .LBB0_3543
	s_barrier
	v_lshl_or_b32 v144, s5, 8, v176
	s_cmpk_eq_i32 s69, 0xc0
	s_mov_b64 s[38:39], -1
	s_cbranch_scc0 .LBB0_3544
